# scan step: two counted LDS waits per step (A,K,V at the top; B,W,R before the state update) instead of four
# speedup vs baseline: 1.0023x; 1.0023x over previous
; DI float oct_sum(float v) { v += dpp_f<0xB1>(v); v += dpp_f<0x4E>(v); v += dpp_f<0x141>(v); return v; }
; DI void scan_item(const Params& p, int b, int h, int half, char* smem, unsigned* pgen, unsigned kp) {
;     ...
;     for (int sg = 0; sg < SC; sg += 4) {
;       float yy[4];
; #pragma unroll
;       for (int s4 = 0; s4 < 4; ++s4) {
;         const int s = sg + s4;
;         const f32x2* a2 = (const f32x2*)(Al + s * 64 + cg * 8);
;         const f32x2* w2 = (const f32x2*)(Wl + s * 64 + cg * 8);
;         const f32x2* b2 = (const f32x2*)(Bl + s * 64 + cg * 8);
;         const f32x2* k2 = (const f32x2*)(Kl + s * 64 + cg * 8);
;         const f32x2* r2 = (const f32x2*)(Rl + s * 64 + cg * 8);
;         f32x2 o[20];
; #pragma unroll
;         for (int i = 0; i < 4; ++i) { o[i] = a2[i]; o[4 + i] = w2[i]; o[8 + i] = b2[i]; o[12 + i] = k2[i]; o[16 + i] = r2[i]; }
;         const float vr = Vl[s * 64 + 32 * half + rp];
;         f32x2 p0 = St[0] * o[0], p1 = St[1] * o[1];
;         p0 = __builtin_elementwise_fma(St[2], o[2], p0); p1 = __builtin_elementwise_fma(St[3], o[3], p1);
;         const float sa = oct_sum((p0.x + p0.y) + (p1.x + p1.y));
;         const f32x2 sv = {sa, sa}, vv = {vr, vr};
;         f32x2 y0 = {0.f, 0.f}, y1 = {0.f, 0.f};
; #pragma unroll
;         for (int i = 0; i < 4; i += 2) {
;           St[i] = __builtin_elementwise_fma(St[i], o[4 + i], __builtin_elementwise_fma(sv, o[8 + i], vv * o[12 + i]));
;           St[i + 1] = __builtin_elementwise_fma(St[i + 1], o[5 + i], __builtin_elementwise_fma(sv, o[9 + i], vv * o[13 + i]));
;           y0 = __builtin_elementwise_fma(St[i], o[16 + i], y0);
;           y1 = __builtin_elementwise_fma(St[i + 1], o[17 + i], y1);
;         }
;         yy[s4] = oct_sum((y0.x + y0.y) + (y1.x + y1.y));
;       }
;       if (cg == 0) {
; #pragma unroll
;         for (int s4 = 0; s4 < 4; ++s4) Yl[(sg + s4) * 32 + rp] = yy[s4];
.LBB0_701:
	s_mov_b32 s26, -4
	v_mov_b32_e32 v0, v214
	v_mov_b32_e32 v161, v160
	v_lshlrev_b32_e32 v162, 2, v173
	v_add_u32_e32 v162, 0xb000, v162
	v_cndmask_b32_e64 v162, v162, v225, s[12:13]
	ds_read_b128 v[34:37], v0 offset:16384
	ds_read_b128 v[38:41], v0 offset:16400
	ds_read_b128 v[68:71], v0 offset:8192
	ds_read_b128 v[150:153], v0 offset:8208
	ds_read2st64_b32 v[158:159], v161 offset0:0 offset1:1
	ds_read_b128 v[50:53], v0 offset:20480
	ds_read_b128 v[54:57], v0 offset:20496
	ds_read_b128 v[42:45], v0 offset:4096
	ds_read_b128 v[46:49], v0 offset:4112
	ds_read_b128 v[154:157], v0 offset:0
	ds_read_b128 v[246:249], v0 offset:16
	ds_read_b128 v[200:203], v0 offset:16640
	ds_read_b128 v[230:233], v0 offset:16656
	s_waitcnt lgkmcnt(8)
	v_pk_mul_f32 v[34:35], v[66:67], v[34:35]
	v_pk_mul_f32 v[36:37], v[64:65], v[36:37]
	v_pk_fma_f32 v[34:35], v[62:63], v[38:39], v[34:35]
	v_pk_fma_f32 v[36:37], v[60:61], v[40:41], v[36:37]
	v_pk_add_f32 v[34:35], v[34:35], v[36:37]
	v_add_f32_e32 v198, v34, v35
	v_pk_mul_f32 v[58:59], v[68:69], v[158:159] op_sel_hi:[1,0]
	v_pk_mul_f32 v[72:73], v[70:71], v[158:159] op_sel_hi:[1,0]
	ds_read_b128 v[68:71], v0 offset:8448
	v_add_f32_dpp v198, v198, v198 quad_perm:[1,0,3,2] row_mask:0xf bank_mask:0xf bound_ctrl:1
	s_nop 0
	v_pk_mul_f32 v[212:213], v[150:151], v[158:159] op_sel_hi:[1,0]
	v_add_f32_dpp v198, v198, v198 quad_perm:[2,3,0,1] row_mask:0xf bank_mask:0xf bound_ctrl:1
	s_nop 0
	v_pk_mul_f32 v[250:251], v[152:153], v[158:159] op_sel_hi:[1,0]
	ds_read_b128 v[150:153], v0 offset:8464
	v_add_f32_dpp v198, v198, v198 row_half_mirror row_mask:0xf bank_mask:0xf bound_ctrl:1
	s_waitcnt lgkmcnt(4)
	v_pk_fma_f32 v[58:59], v[198:199], v[50:51], v[58:59] op_sel_hi:[0,1,1]
	v_pk_fma_f32 v[72:73], v[198:199], v[52:53], v[72:73] op_sel_hi:[0,1,1]
	v_pk_fma_f32 v[66:67], v[66:67], v[42:43], v[58:59]
	v_pk_fma_f32 v[64:65], v[64:65], v[44:45], v[72:73]
	v_pk_fma_f32 v[212:213], v[198:199], v[54:55], v[212:213] op_sel_hi:[0,1,1]
	v_pk_fma_f32 v[250:251], v[198:199], v[56:57], v[250:251] op_sel_hi:[0,1,1]
	v_pk_fma_f32 v[62:63], v[62:63], v[46:47], v[212:213]
	v_pk_fma_f32 v[60:61], v[60:61], v[48:49], v[250:251]
	ds_read_b128 v[50:53], v0 offset:20736
	ds_read_b128 v[54:57], v0 offset:20752
	ds_read_b128 v[42:45], v0 offset:4352
	ds_read_b128 v[46:49], v0 offset:4368
	v_pk_fma_f32 v[58:59], v[66:67], v[154:155], 0 op_sel_hi:[1,1,0]
	v_pk_fma_f32 v[72:73], v[64:65], v[156:157], 0 op_sel_hi:[1,1,0]
	v_pk_fma_f32 v[58:59], v[62:63], v[246:247], v[58:59]
	v_pk_fma_f32 v[72:73], v[60:61], v[248:249], v[72:73]
	ds_read_b128 v[154:157], v0 offset:256
	ds_read_b128 v[246:249], v0 offset:272
	v_pk_add_f32 v[58:59], v[58:59], v[72:73]
	ds_read_b128 v[34:37], v0 offset:16896
	ds_read_b128 v[38:41], v0 offset:16912
	s_waitcnt lgkmcnt(8)
	v_pk_mul_f32 v[200:201], v[66:67], v[200:201]
	v_pk_mul_f32 v[202:203], v[64:65], v[202:203]
	v_pk_fma_f32 v[200:201], v[62:63], v[230:231], v[200:201]
	v_pk_fma_f32 v[202:203], v[60:61], v[232:233], v[202:203]
	v_pk_add_f32 v[200:201], v[200:201], v[202:203]
	v_add_f32_e32 v207, v58, v59
	v_add_f32_e32 v198, v200, v201
	v_mov_b32_e32 v232, v159
	v_pk_mul_f32 v[58:59], v[68:69], v[232:233] op_sel_hi:[1,0]
	v_pk_mul_f32 v[72:73], v[70:71], v[232:233] op_sel_hi:[1,0]
	ds_read_b128 v[68:71], v0 offset:8704
	v_add_f32_dpp v198, v198, v198 quad_perm:[1,0,3,2] row_mask:0xf bank_mask:0xf bound_ctrl:1
	v_add_f32_dpp v207, v207, v207 quad_perm:[1,0,3,2] row_mask:0xf bank_mask:0xf bound_ctrl:1
	v_pk_mul_f32 v[212:213], v[150:151], v[232:233] op_sel_hi:[1,0]
	v_add_f32_dpp v198, v198, v198 quad_perm:[2,3,0,1] row_mask:0xf bank_mask:0xf bound_ctrl:1
	v_add_f32_dpp v207, v207, v207 quad_perm:[2,3,0,1] row_mask:0xf bank_mask:0xf bound_ctrl:1
	v_pk_mul_f32 v[250:251], v[152:153], v[232:233] op_sel_hi:[1,0]
	ds_read_b128 v[150:153], v0 offset:8720
	v_add_f32_dpp v198, v198, v198 row_half_mirror row_mask:0xf bank_mask:0xf bound_ctrl:1
	v_add_f32_dpp v163, v207, v207 row_half_mirror row_mask:0xf bank_mask:0xf bound_ctrl:1
	ds_read2st64_b32 v[158:159], v161 offset0:2 offset1:3
	ds_write_b32 v162, v163 offset:0
	s_waitcnt lgkmcnt(5)
	v_pk_fma_f32 v[58:59], v[198:199], v[50:51], v[58:59] op_sel_hi:[0,1,1]
	v_pk_fma_f32 v[72:73], v[198:199], v[52:53], v[72:73] op_sel_hi:[0,1,1]
	v_pk_fma_f32 v[66:67], v[66:67], v[42:43], v[58:59]
	v_pk_fma_f32 v[64:65], v[64:65], v[44:45], v[72:73]
	v_pk_fma_f32 v[212:213], v[198:199], v[54:55], v[212:213] op_sel_hi:[0,1,1]
	v_pk_fma_f32 v[250:251], v[198:199], v[56:57], v[250:251] op_sel_hi:[0,1,1]
	v_pk_fma_f32 v[62:63], v[62:63], v[46:47], v[212:213]
	v_pk_fma_f32 v[60:61], v[60:61], v[48:49], v[250:251]
	ds_read_b128 v[50:53], v0 offset:20992
	ds_read_b128 v[54:57], v0 offset:21008
	ds_read_b128 v[42:45], v0 offset:4608
	ds_read_b128 v[46:49], v0 offset:4624
	v_pk_fma_f32 v[58:59], v[66:67], v[154:155], 0 op_sel_hi:[1,1,0]
	v_pk_fma_f32 v[72:73], v[64:65], v[156:157], 0 op_sel_hi:[1,1,0]
	v_pk_fma_f32 v[58:59], v[62:63], v[246:247], v[58:59]
	v_pk_fma_f32 v[72:73], v[60:61], v[248:249], v[72:73]
	ds_read_b128 v[154:157], v0 offset:512
	ds_read_b128 v[246:249], v0 offset:528
	v_pk_add_f32 v[58:59], v[58:59], v[72:73]
	ds_read_b128 v[200:203], v0 offset:17152
	ds_read_b128 v[230:233], v0 offset:17168
	s_waitcnt lgkmcnt(8)
; DI float oct_sum(float v) { v += dpp_f<0xB1>(v); v += dpp_f<0x4E>(v); v += dpp_f<0x141>(v); return v; }
; DI void scan_item(const Params& p, int b, int h, int half, char* smem, unsigned* pgen, unsigned kp) {
;     ...
;       for (int s4 = 0; s4 < 4; ++s4) {
;         const int s = sg + s4;
;         const f32x2* a2 = (const f32x2*)(Al + s * 64 + cg * 8);
;         const f32x2* w2 = (const f32x2*)(Wl + s * 64 + cg * 8);
;         const f32x2* b2 = (const f32x2*)(Bl + s * 64 + cg * 8);
;         const f32x2* k2 = (const f32x2*)(Kl + s * 64 + cg * 8);
;         const f32x2* r2 = (const f32x2*)(Rl + s * 64 + cg * 8);
;         f32x2 o[20];
; #pragma unroll
;         for (int i = 0; i < 4; ++i) { o[i] = a2[i]; o[4 + i] = w2[i]; o[8 + i] = b2[i]; o[12 + i] = k2[i]; o[16 + i] = r2[i]; }
;         const float vr = Vl[s * 64 + 32 * half + rp];
;         f32x2 p0 = St[0] * o[0], p1 = St[1] * o[1];
;         p0 = __builtin_elementwise_fma(St[2], o[2], p0); p1 = __builtin_elementwise_fma(St[3], o[3], p1);
;         const float sa = oct_sum((p0.x + p0.y) + (p1.x + p1.y));
;         const f32x2 sv = {sa, sa}, vv = {vr, vr};
;         f32x2 y0 = {0.f, 0.f}, y1 = {0.f, 0.f};
; #pragma unroll
;         for (int i = 0; i < 4; i += 2) {
;           St[i] = __builtin_elementwise_fma(St[i], o[4 + i], __builtin_elementwise_fma(sv, o[8 + i], vv * o[12 + i]));
;           St[i + 1] = __builtin_elementwise_fma(St[i + 1], o[5 + i], __builtin_elementwise_fma(sv, o[9 + i], vv * o[13 + i]));
;           y0 = __builtin_elementwise_fma(St[i], o[16 + i], y0);
;           y1 = __builtin_elementwise_fma(St[i + 1], o[17 + i], y1);
;         }
;         yy[s4] = oct_sum((y0.x + y0.y) + (y1.x + y1.y));
;       }
;       if (cg == 0) {
; #pragma unroll
;         for (int s4 = 0; s4 < 4; ++s4) Yl[(sg + s4) * 32 + rp] = yy[s4];
	v_pk_mul_f32 v[34:35], v[66:67], v[34:35]
	v_pk_mul_f32 v[36:37], v[64:65], v[36:37]
	v_pk_fma_f32 v[34:35], v[62:63], v[38:39], v[34:35]
	v_pk_fma_f32 v[36:37], v[60:61], v[40:41], v[36:37]
	v_pk_add_f32 v[34:35], v[34:35], v[36:37]
	v_add_f32_e32 v207, v58, v59
	v_add_f32_e32 v198, v34, v35
	v_pk_mul_f32 v[58:59], v[68:69], v[158:159] op_sel_hi:[1,0]
	v_pk_mul_f32 v[72:73], v[70:71], v[158:159] op_sel_hi:[1,0]
	ds_read_b128 v[68:71], v0 offset:8960
	v_add_f32_dpp v198, v198, v198 quad_perm:[1,0,3,2] row_mask:0xf bank_mask:0xf bound_ctrl:1
	v_add_f32_dpp v207, v207, v207 quad_perm:[1,0,3,2] row_mask:0xf bank_mask:0xf bound_ctrl:1
	v_pk_mul_f32 v[212:213], v[150:151], v[158:159] op_sel_hi:[1,0]
	v_add_f32_dpp v198, v198, v198 quad_perm:[2,3,0,1] row_mask:0xf bank_mask:0xf bound_ctrl:1
	v_add_f32_dpp v207, v207, v207 quad_perm:[2,3,0,1] row_mask:0xf bank_mask:0xf bound_ctrl:1
	v_pk_mul_f32 v[250:251], v[152:153], v[158:159] op_sel_hi:[1,0]
	ds_read_b128 v[150:153], v0 offset:8976
	v_add_f32_dpp v198, v198, v198 row_half_mirror row_mask:0xf bank_mask:0xf bound_ctrl:1
	v_add_f32_dpp v205, v207, v207 row_half_mirror row_mask:0xf bank_mask:0xf bound_ctrl:1
	ds_write_b32 v162, v205 offset:128
	s_waitcnt lgkmcnt(4)
	v_pk_fma_f32 v[58:59], v[198:199], v[50:51], v[58:59] op_sel_hi:[0,1,1]
	v_pk_fma_f32 v[72:73], v[198:199], v[52:53], v[72:73] op_sel_hi:[0,1,1]
	v_pk_fma_f32 v[66:67], v[66:67], v[42:43], v[58:59]
	v_pk_fma_f32 v[64:65], v[64:65], v[44:45], v[72:73]
	v_pk_fma_f32 v[212:213], v[198:199], v[54:55], v[212:213] op_sel_hi:[0,1,1]
	v_pk_fma_f32 v[250:251], v[198:199], v[56:57], v[250:251] op_sel_hi:[0,1,1]
	v_pk_fma_f32 v[62:63], v[62:63], v[46:47], v[212:213]
	v_pk_fma_f32 v[60:61], v[60:61], v[48:49], v[250:251]
	ds_read_b128 v[50:53], v0 offset:21248
	ds_read_b128 v[54:57], v0 offset:21264
	ds_read_b128 v[42:45], v0 offset:4864
	ds_read_b128 v[46:49], v0 offset:4880
	v_pk_fma_f32 v[58:59], v[66:67], v[154:155], 0 op_sel_hi:[1,1,0]
	v_pk_fma_f32 v[72:73], v[64:65], v[156:157], 0 op_sel_hi:[1,1,0]
	v_pk_fma_f32 v[58:59], v[62:63], v[246:247], v[58:59]
	v_pk_fma_f32 v[72:73], v[60:61], v[248:249], v[72:73]
	ds_read_b128 v[154:157], v0 offset:768
	ds_read_b128 v[246:249], v0 offset:784
	v_pk_add_f32 v[58:59], v[58:59], v[72:73]
	ds_read_b128 v[34:37], v0 offset:17408
	ds_read_b128 v[38:41], v0 offset:17424
	s_waitcnt lgkmcnt(8)
	v_pk_mul_f32 v[200:201], v[66:67], v[200:201]
	v_pk_mul_f32 v[202:203], v[64:65], v[202:203]
	v_pk_fma_f32 v[200:201], v[62:63], v[230:231], v[200:201]
	v_pk_fma_f32 v[202:203], v[60:61], v[232:233], v[202:203]
	v_pk_add_f32 v[200:201], v[200:201], v[202:203]
	v_add_f32_e32 v207, v58, v59
	v_add_f32_e32 v198, v200, v201
	v_mov_b32_e32 v232, v159
	v_pk_mul_f32 v[58:59], v[68:69], v[232:233] op_sel_hi:[1,0]
	v_pk_mul_f32 v[72:73], v[70:71], v[232:233] op_sel_hi:[1,0]
	ds_read_b128 v[68:71], v0 offset:9216
	v_add_f32_dpp v198, v198, v198 quad_perm:[1,0,3,2] row_mask:0xf bank_mask:0xf bound_ctrl:1
	v_add_f32_dpp v207, v207, v207 quad_perm:[1,0,3,2] row_mask:0xf bank_mask:0xf bound_ctrl:1
	v_pk_mul_f32 v[212:213], v[150:151], v[232:233] op_sel_hi:[1,0]
	v_add_f32_dpp v198, v198, v198 quad_perm:[2,3,0,1] row_mask:0xf bank_mask:0xf bound_ctrl:1
	v_add_f32_dpp v207, v207, v207 quad_perm:[2,3,0,1] row_mask:0xf bank_mask:0xf bound_ctrl:1
	v_pk_mul_f32 v[250:251], v[152:153], v[232:233] op_sel_hi:[1,0]
	ds_read_b128 v[150:153], v0 offset:9232
	v_add_f32_dpp v198, v198, v198 row_half_mirror row_mask:0xf bank_mask:0xf bound_ctrl:1
	v_add_f32_dpp v163, v207, v207 row_half_mirror row_mask:0xf bank_mask:0xf bound_ctrl:1
	ds_read2st64_b32 v[158:159], v161 offset0:4 offset1:5
	ds_write_b32 v162, v163 offset:256
	s_waitcnt lgkmcnt(5)
	v_pk_fma_f32 v[58:59], v[198:199], v[50:51], v[58:59] op_sel_hi:[0,1,1]
	v_pk_fma_f32 v[72:73], v[198:199], v[52:53], v[72:73] op_sel_hi:[0,1,1]
	v_pk_fma_f32 v[66:67], v[66:67], v[42:43], v[58:59]
	v_pk_fma_f32 v[64:65], v[64:65], v[44:45], v[72:73]
	v_pk_fma_f32 v[212:213], v[198:199], v[54:55], v[212:213] op_sel_hi:[0,1,1]
	v_pk_fma_f32 v[250:251], v[198:199], v[56:57], v[250:251] op_sel_hi:[0,1,1]
	v_pk_fma_f32 v[62:63], v[62:63], v[46:47], v[212:213]
	v_pk_fma_f32 v[60:61], v[60:61], v[48:49], v[250:251]
	ds_read_b128 v[50:53], v0 offset:21504
	ds_read_b128 v[54:57], v0 offset:21520
	ds_read_b128 v[42:45], v0 offset:5120
	ds_read_b128 v[46:49], v0 offset:5136
	v_pk_fma_f32 v[58:59], v[66:67], v[154:155], 0 op_sel_hi:[1,1,0]
	v_pk_fma_f32 v[72:73], v[64:65], v[156:157], 0 op_sel_hi:[1,1,0]
	v_pk_fma_f32 v[58:59], v[62:63], v[246:247], v[58:59]
	v_pk_fma_f32 v[72:73], v[60:61], v[248:249], v[72:73]
	ds_read_b128 v[154:157], v0 offset:1024
	ds_read_b128 v[246:249], v0 offset:1040
	v_pk_add_f32 v[58:59], v[58:59], v[72:73]
	ds_read_b128 v[200:203], v0 offset:17664
	ds_read_b128 v[230:233], v0 offset:17680
	s_waitcnt lgkmcnt(8)
	v_pk_mul_f32 v[34:35], v[66:67], v[34:35]
	v_pk_mul_f32 v[36:37], v[64:65], v[36:37]
	v_pk_fma_f32 v[34:35], v[62:63], v[38:39], v[34:35]
	v_pk_fma_f32 v[36:37], v[60:61], v[40:41], v[36:37]
	v_pk_add_f32 v[34:35], v[34:35], v[36:37]
	v_add_f32_e32 v207, v58, v59
	v_add_f32_e32 v198, v34, v35
	v_pk_mul_f32 v[58:59], v[68:69], v[158:159] op_sel_hi:[1,0]
	v_pk_mul_f32 v[72:73], v[70:71], v[158:159] op_sel_hi:[1,0]
	ds_read_b128 v[68:71], v0 offset:9472
	v_add_f32_dpp v198, v198, v198 quad_perm:[1,0,3,2] row_mask:0xf bank_mask:0xf bound_ctrl:1
	v_add_f32_dpp v207, v207, v207 quad_perm:[1,0,3,2] row_mask:0xf bank_mask:0xf bound_ctrl:1
	v_pk_mul_f32 v[212:213], v[150:151], v[158:159] op_sel_hi:[1,0]
	v_add_f32_dpp v198, v198, v198 quad_perm:[2,3,0,1] row_mask:0xf bank_mask:0xf bound_ctrl:1
	v_add_f32_dpp v207, v207, v207 quad_perm:[2,3,0,1] row_mask:0xf bank_mask:0xf bound_ctrl:1
	v_pk_mul_f32 v[250:251], v[152:153], v[158:159] op_sel_hi:[1,0]
	ds_read_b128 v[150:153], v0 offset:9488
	v_add_f32_dpp v198, v198, v198 row_half_mirror row_mask:0xf bank_mask:0xf bound_ctrl:1
	v_add_f32_dpp v205, v207, v207 row_half_mirror row_mask:0xf bank_mask:0xf bound_ctrl:1
	ds_write_b32 v162, v205 offset:384
	s_waitcnt lgkmcnt(4)
; DI float oct_sum(float v) { v += dpp_f<0xB1>(v); v += dpp_f<0x4E>(v); v += dpp_f<0x141>(v); return v; }
; DI void scan_item(const Params& p, int b, int h, int half, char* smem, unsigned* pgen, unsigned kp) {
;     ...
;       for (int s4 = 0; s4 < 4; ++s4) {
;         const int s = sg + s4;
;         const f32x2* a2 = (const f32x2*)(Al + s * 64 + cg * 8);
;         const f32x2* w2 = (const f32x2*)(Wl + s * 64 + cg * 8);
;         const f32x2* b2 = (const f32x2*)(Bl + s * 64 + cg * 8);
;         const f32x2* k2 = (const f32x2*)(Kl + s * 64 + cg * 8);
;         const f32x2* r2 = (const f32x2*)(Rl + s * 64 + cg * 8);
;         f32x2 o[20];
; #pragma unroll
;         for (int i = 0; i < 4; ++i) { o[i] = a2[i]; o[4 + i] = w2[i]; o[8 + i] = b2[i]; o[12 + i] = k2[i]; o[16 + i] = r2[i]; }
;         const float vr = Vl[s * 64 + 32 * half + rp];
;         f32x2 p0 = St[0] * o[0], p1 = St[1] * o[1];
;         p0 = __builtin_elementwise_fma(St[2], o[2], p0); p1 = __builtin_elementwise_fma(St[3], o[3], p1);
;         const float sa = oct_sum((p0.x + p0.y) + (p1.x + p1.y));
;         const f32x2 sv = {sa, sa}, vv = {vr, vr};
;         f32x2 y0 = {0.f, 0.f}, y1 = {0.f, 0.f};
; #pragma unroll
;         for (int i = 0; i < 4; i += 2) {
;           St[i] = __builtin_elementwise_fma(St[i], o[4 + i], __builtin_elementwise_fma(sv, o[8 + i], vv * o[12 + i]));
;           St[i + 1] = __builtin_elementwise_fma(St[i + 1], o[5 + i], __builtin_elementwise_fma(sv, o[9 + i], vv * o[13 + i]));
;           y0 = __builtin_elementwise_fma(St[i], o[16 + i], y0);
;           y1 = __builtin_elementwise_fma(St[i + 1], o[17 + i], y1);
;         }
;         yy[s4] = oct_sum((y0.x + y0.y) + (y1.x + y1.y));
;       }
;       if (cg == 0) {
; #pragma unroll
;         for (int s4 = 0; s4 < 4; ++s4) Yl[(sg + s4) * 32 + rp] = yy[s4];
	v_pk_fma_f32 v[58:59], v[198:199], v[50:51], v[58:59] op_sel_hi:[0,1,1]
	v_pk_fma_f32 v[72:73], v[198:199], v[52:53], v[72:73] op_sel_hi:[0,1,1]
	v_pk_fma_f32 v[66:67], v[66:67], v[42:43], v[58:59]
	v_pk_fma_f32 v[64:65], v[64:65], v[44:45], v[72:73]
	v_pk_fma_f32 v[212:213], v[198:199], v[54:55], v[212:213] op_sel_hi:[0,1,1]
	v_pk_fma_f32 v[250:251], v[198:199], v[56:57], v[250:251] op_sel_hi:[0,1,1]
	v_pk_fma_f32 v[62:63], v[62:63], v[46:47], v[212:213]
	v_pk_fma_f32 v[60:61], v[60:61], v[48:49], v[250:251]
	ds_read_b128 v[50:53], v0 offset:21760
	ds_read_b128 v[54:57], v0 offset:21776
	ds_read_b128 v[42:45], v0 offset:5376
	ds_read_b128 v[46:49], v0 offset:5392
	v_pk_fma_f32 v[58:59], v[66:67], v[154:155], 0 op_sel_hi:[1,1,0]
	v_pk_fma_f32 v[72:73], v[64:65], v[156:157], 0 op_sel_hi:[1,1,0]
	v_pk_fma_f32 v[58:59], v[62:63], v[246:247], v[58:59]
	v_pk_fma_f32 v[72:73], v[60:61], v[248:249], v[72:73]
	ds_read_b128 v[154:157], v0 offset:1280
	ds_read_b128 v[246:249], v0 offset:1296
	v_pk_add_f32 v[58:59], v[58:59], v[72:73]
	ds_read_b128 v[34:37], v0 offset:17920
	ds_read_b128 v[38:41], v0 offset:17936
	s_waitcnt lgkmcnt(8)
	v_pk_mul_f32 v[200:201], v[66:67], v[200:201]
	v_pk_mul_f32 v[202:203], v[64:65], v[202:203]
	v_pk_fma_f32 v[200:201], v[62:63], v[230:231], v[200:201]
	v_pk_fma_f32 v[202:203], v[60:61], v[232:233], v[202:203]
	v_pk_add_f32 v[200:201], v[200:201], v[202:203]
	v_add_f32_e32 v207, v58, v59
	v_add_f32_e32 v198, v200, v201
	v_mov_b32_e32 v232, v159
	v_pk_mul_f32 v[58:59], v[68:69], v[232:233] op_sel_hi:[1,0]
	v_pk_mul_f32 v[72:73], v[70:71], v[232:233] op_sel_hi:[1,0]
	ds_read_b128 v[68:71], v0 offset:9728
	v_add_f32_dpp v198, v198, v198 quad_perm:[1,0,3,2] row_mask:0xf bank_mask:0xf bound_ctrl:1
	v_add_f32_dpp v207, v207, v207 quad_perm:[1,0,3,2] row_mask:0xf bank_mask:0xf bound_ctrl:1
	v_pk_mul_f32 v[212:213], v[150:151], v[232:233] op_sel_hi:[1,0]
	v_add_f32_dpp v198, v198, v198 quad_perm:[2,3,0,1] row_mask:0xf bank_mask:0xf bound_ctrl:1
	v_add_f32_dpp v207, v207, v207 quad_perm:[2,3,0,1] row_mask:0xf bank_mask:0xf bound_ctrl:1
	v_pk_mul_f32 v[250:251], v[152:153], v[232:233] op_sel_hi:[1,0]
	ds_read_b128 v[150:153], v0 offset:9744
	v_add_f32_dpp v198, v198, v198 row_half_mirror row_mask:0xf bank_mask:0xf bound_ctrl:1
	v_add_f32_dpp v163, v207, v207 row_half_mirror row_mask:0xf bank_mask:0xf bound_ctrl:1
	ds_read2st64_b32 v[158:159], v161 offset0:6 offset1:7
	ds_write_b32 v162, v163 offset:512
	s_waitcnt lgkmcnt(5)
	v_pk_fma_f32 v[58:59], v[198:199], v[50:51], v[58:59] op_sel_hi:[0,1,1]
	v_pk_fma_f32 v[72:73], v[198:199], v[52:53], v[72:73] op_sel_hi:[0,1,1]
	v_pk_fma_f32 v[66:67], v[66:67], v[42:43], v[58:59]
	v_pk_fma_f32 v[64:65], v[64:65], v[44:45], v[72:73]
	v_pk_fma_f32 v[212:213], v[198:199], v[54:55], v[212:213] op_sel_hi:[0,1,1]
	v_pk_fma_f32 v[250:251], v[198:199], v[56:57], v[250:251] op_sel_hi:[0,1,1]
	v_pk_fma_f32 v[62:63], v[62:63], v[46:47], v[212:213]
	v_pk_fma_f32 v[60:61], v[60:61], v[48:49], v[250:251]
	ds_read_b128 v[50:53], v0 offset:22016
	ds_read_b128 v[54:57], v0 offset:22032
	ds_read_b128 v[42:45], v0 offset:5632
	ds_read_b128 v[46:49], v0 offset:5648
	v_pk_fma_f32 v[58:59], v[66:67], v[154:155], 0 op_sel_hi:[1,1,0]
	v_pk_fma_f32 v[72:73], v[64:65], v[156:157], 0 op_sel_hi:[1,1,0]
	v_pk_fma_f32 v[58:59], v[62:63], v[246:247], v[58:59]
	v_pk_fma_f32 v[72:73], v[60:61], v[248:249], v[72:73]
	ds_read_b128 v[154:157], v0 offset:1536
	ds_read_b128 v[246:249], v0 offset:1552
	v_pk_add_f32 v[58:59], v[58:59], v[72:73]
	ds_read_b128 v[200:203], v0 offset:18176
	ds_read_b128 v[230:233], v0 offset:18192
	s_waitcnt lgkmcnt(8)
	v_pk_mul_f32 v[34:35], v[66:67], v[34:35]
	v_pk_mul_f32 v[36:37], v[64:65], v[36:37]
	v_pk_fma_f32 v[34:35], v[62:63], v[38:39], v[34:35]
	v_pk_fma_f32 v[36:37], v[60:61], v[40:41], v[36:37]
	v_pk_add_f32 v[34:35], v[34:35], v[36:37]
	v_add_f32_e32 v207, v58, v59
	v_add_f32_e32 v198, v34, v35
	v_pk_mul_f32 v[58:59], v[68:69], v[158:159] op_sel_hi:[1,0]
	v_pk_mul_f32 v[72:73], v[70:71], v[158:159] op_sel_hi:[1,0]
	ds_read_b128 v[68:71], v0 offset:9984
	v_add_f32_dpp v198, v198, v198 quad_perm:[1,0,3,2] row_mask:0xf bank_mask:0xf bound_ctrl:1
	v_add_f32_dpp v207, v207, v207 quad_perm:[1,0,3,2] row_mask:0xf bank_mask:0xf bound_ctrl:1
	v_pk_mul_f32 v[212:213], v[150:151], v[158:159] op_sel_hi:[1,0]
	v_add_f32_dpp v198, v198, v198 quad_perm:[2,3,0,1] row_mask:0xf bank_mask:0xf bound_ctrl:1
	v_add_f32_dpp v207, v207, v207 quad_perm:[2,3,0,1] row_mask:0xf bank_mask:0xf bound_ctrl:1
	v_pk_mul_f32 v[250:251], v[152:153], v[158:159] op_sel_hi:[1,0]
	ds_read_b128 v[150:153], v0 offset:10000
	v_add_f32_dpp v198, v198, v198 row_half_mirror row_mask:0xf bank_mask:0xf bound_ctrl:1
	v_add_f32_dpp v205, v207, v207 row_half_mirror row_mask:0xf bank_mask:0xf bound_ctrl:1
	ds_write_b32 v162, v205 offset:640
	s_waitcnt lgkmcnt(4)
	v_pk_fma_f32 v[58:59], v[198:199], v[50:51], v[58:59] op_sel_hi:[0,1,1]
	v_pk_fma_f32 v[72:73], v[198:199], v[52:53], v[72:73] op_sel_hi:[0,1,1]
	v_pk_fma_f32 v[66:67], v[66:67], v[42:43], v[58:59]
	v_pk_fma_f32 v[64:65], v[64:65], v[44:45], v[72:73]
	v_pk_fma_f32 v[212:213], v[198:199], v[54:55], v[212:213] op_sel_hi:[0,1,1]
	v_pk_fma_f32 v[250:251], v[198:199], v[56:57], v[250:251] op_sel_hi:[0,1,1]
	v_pk_fma_f32 v[62:63], v[62:63], v[46:47], v[212:213]
	v_pk_fma_f32 v[60:61], v[60:61], v[48:49], v[250:251]
	ds_read_b128 v[50:53], v0 offset:22272
	ds_read_b128 v[54:57], v0 offset:22288
	ds_read_b128 v[42:45], v0 offset:5888
	ds_read_b128 v[46:49], v0 offset:5904
	v_pk_fma_f32 v[58:59], v[66:67], v[154:155], 0 op_sel_hi:[1,1,0]
	v_pk_fma_f32 v[72:73], v[64:65], v[156:157], 0 op_sel_hi:[1,1,0]
	v_pk_fma_f32 v[58:59], v[62:63], v[246:247], v[58:59]
	v_pk_fma_f32 v[72:73], v[60:61], v[248:249], v[72:73]
	ds_read_b128 v[154:157], v0 offset:1792
	ds_read_b128 v[246:249], v0 offset:1808
	v_pk_add_f32 v[58:59], v[58:59], v[72:73]
	ds_read_b128 v[34:37], v0 offset:18432
	ds_read_b128 v[38:41], v0 offset:18448
	s_waitcnt lgkmcnt(8)
; DI float oct_sum(float v) { v += dpp_f<0xB1>(v); v += dpp_f<0x4E>(v); v += dpp_f<0x141>(v); return v; }
; DI void scan_item(const Params& p, int b, int h, int half, char* smem, unsigned* pgen, unsigned kp) {
;     ...
;       for (int s4 = 0; s4 < 4; ++s4) {
;         const int s = sg + s4;
;         const f32x2* a2 = (const f32x2*)(Al + s * 64 + cg * 8);
;         const f32x2* w2 = (const f32x2*)(Wl + s * 64 + cg * 8);
;         const f32x2* b2 = (const f32x2*)(Bl + s * 64 + cg * 8);
;         const f32x2* k2 = (const f32x2*)(Kl + s * 64 + cg * 8);
;         const f32x2* r2 = (const f32x2*)(Rl + s * 64 + cg * 8);
;         f32x2 o[20];
; #pragma unroll
;         for (int i = 0; i < 4; ++i) { o[i] = a2[i]; o[4 + i] = w2[i]; o[8 + i] = b2[i]; o[12 + i] = k2[i]; o[16 + i] = r2[i]; }
;         const float vr = Vl[s * 64 + 32 * half + rp];
;         f32x2 p0 = St[0] * o[0], p1 = St[1] * o[1];
;         p0 = __builtin_elementwise_fma(St[2], o[2], p0); p1 = __builtin_elementwise_fma(St[3], o[3], p1);
;         const float sa = oct_sum((p0.x + p0.y) + (p1.x + p1.y));
;         const f32x2 sv = {sa, sa}, vv = {vr, vr};
;         f32x2 y0 = {0.f, 0.f}, y1 = {0.f, 0.f};
; #pragma unroll
;         for (int i = 0; i < 4; i += 2) {
;           St[i] = __builtin_elementwise_fma(St[i], o[4 + i], __builtin_elementwise_fma(sv, o[8 + i], vv * o[12 + i]));
;           St[i + 1] = __builtin_elementwise_fma(St[i + 1], o[5 + i], __builtin_elementwise_fma(sv, o[9 + i], vv * o[13 + i]));
;           y0 = __builtin_elementwise_fma(St[i], o[16 + i], y0);
;           y1 = __builtin_elementwise_fma(St[i + 1], o[17 + i], y1);
;         }
;         yy[s4] = oct_sum((y0.x + y0.y) + (y1.x + y1.y));
;       }
;       if (cg == 0) {
; #pragma unroll
;         for (int s4 = 0; s4 < 4; ++s4) Yl[(sg + s4) * 32 + rp] = yy[s4];
	v_pk_mul_f32 v[200:201], v[66:67], v[200:201]
	v_pk_mul_f32 v[202:203], v[64:65], v[202:203]
	v_pk_fma_f32 v[200:201], v[62:63], v[230:231], v[200:201]
	v_pk_fma_f32 v[202:203], v[60:61], v[232:233], v[202:203]
	v_pk_add_f32 v[200:201], v[200:201], v[202:203]
	v_add_f32_e32 v207, v58, v59
	v_add_f32_e32 v198, v200, v201
	v_mov_b32_e32 v232, v159
	v_pk_mul_f32 v[58:59], v[68:69], v[232:233] op_sel_hi:[1,0]
	v_pk_mul_f32 v[72:73], v[70:71], v[232:233] op_sel_hi:[1,0]
	ds_read_b128 v[68:71], v0 offset:10240
	v_add_f32_dpp v198, v198, v198 quad_perm:[1,0,3,2] row_mask:0xf bank_mask:0xf bound_ctrl:1
	v_add_f32_dpp v207, v207, v207 quad_perm:[1,0,3,2] row_mask:0xf bank_mask:0xf bound_ctrl:1
	v_pk_mul_f32 v[212:213], v[150:151], v[232:233] op_sel_hi:[1,0]
	v_add_f32_dpp v198, v198, v198 quad_perm:[2,3,0,1] row_mask:0xf bank_mask:0xf bound_ctrl:1
	v_add_f32_dpp v207, v207, v207 quad_perm:[2,3,0,1] row_mask:0xf bank_mask:0xf bound_ctrl:1
	v_pk_mul_f32 v[250:251], v[152:153], v[232:233] op_sel_hi:[1,0]
	ds_read_b128 v[150:153], v0 offset:10256
	v_add_f32_dpp v198, v198, v198 row_half_mirror row_mask:0xf bank_mask:0xf bound_ctrl:1
	v_add_f32_dpp v163, v207, v207 row_half_mirror row_mask:0xf bank_mask:0xf bound_ctrl:1
	ds_read2st64_b32 v[158:159], v161 offset0:8 offset1:9
	ds_write_b32 v162, v163 offset:768
	s_waitcnt lgkmcnt(5)
	v_pk_fma_f32 v[58:59], v[198:199], v[50:51], v[58:59] op_sel_hi:[0,1,1]
	v_pk_fma_f32 v[72:73], v[198:199], v[52:53], v[72:73] op_sel_hi:[0,1,1]
	v_pk_fma_f32 v[66:67], v[66:67], v[42:43], v[58:59]
	v_pk_fma_f32 v[64:65], v[64:65], v[44:45], v[72:73]
	v_pk_fma_f32 v[212:213], v[198:199], v[54:55], v[212:213] op_sel_hi:[0,1,1]
	v_pk_fma_f32 v[250:251], v[198:199], v[56:57], v[250:251] op_sel_hi:[0,1,1]
	v_pk_fma_f32 v[62:63], v[62:63], v[46:47], v[212:213]
	v_pk_fma_f32 v[60:61], v[60:61], v[48:49], v[250:251]
	ds_read_b128 v[50:53], v0 offset:22528
	ds_read_b128 v[54:57], v0 offset:22544
	ds_read_b128 v[42:45], v0 offset:6144
	ds_read_b128 v[46:49], v0 offset:6160
	v_pk_fma_f32 v[58:59], v[66:67], v[154:155], 0 op_sel_hi:[1,1,0]
	v_pk_fma_f32 v[72:73], v[64:65], v[156:157], 0 op_sel_hi:[1,1,0]
	v_pk_fma_f32 v[58:59], v[62:63], v[246:247], v[58:59]
	v_pk_fma_f32 v[72:73], v[60:61], v[248:249], v[72:73]
	ds_read_b128 v[154:157], v0 offset:2048
	ds_read_b128 v[246:249], v0 offset:2064
	v_pk_add_f32 v[58:59], v[58:59], v[72:73]
	ds_read_b128 v[200:203], v0 offset:18688
	ds_read_b128 v[230:233], v0 offset:18704
	s_waitcnt lgkmcnt(8)
	v_pk_mul_f32 v[34:35], v[66:67], v[34:35]
	v_pk_mul_f32 v[36:37], v[64:65], v[36:37]
	v_pk_fma_f32 v[34:35], v[62:63], v[38:39], v[34:35]
	v_pk_fma_f32 v[36:37], v[60:61], v[40:41], v[36:37]
	v_pk_add_f32 v[34:35], v[34:35], v[36:37]
	v_add_f32_e32 v207, v58, v59
	v_add_f32_e32 v198, v34, v35
	v_pk_mul_f32 v[58:59], v[68:69], v[158:159] op_sel_hi:[1,0]
	v_pk_mul_f32 v[72:73], v[70:71], v[158:159] op_sel_hi:[1,0]
	ds_read_b128 v[68:71], v0 offset:10496
	v_add_f32_dpp v198, v198, v198 quad_perm:[1,0,3,2] row_mask:0xf bank_mask:0xf bound_ctrl:1
	v_add_f32_dpp v207, v207, v207 quad_perm:[1,0,3,2] row_mask:0xf bank_mask:0xf bound_ctrl:1
	v_pk_mul_f32 v[212:213], v[150:151], v[158:159] op_sel_hi:[1,0]
	v_add_f32_dpp v198, v198, v198 quad_perm:[2,3,0,1] row_mask:0xf bank_mask:0xf bound_ctrl:1
	v_add_f32_dpp v207, v207, v207 quad_perm:[2,3,0,1] row_mask:0xf bank_mask:0xf bound_ctrl:1
	v_pk_mul_f32 v[250:251], v[152:153], v[158:159] op_sel_hi:[1,0]
	ds_read_b128 v[150:153], v0 offset:10512
	v_add_f32_dpp v198, v198, v198 row_half_mirror row_mask:0xf bank_mask:0xf bound_ctrl:1
	v_add_f32_dpp v205, v207, v207 row_half_mirror row_mask:0xf bank_mask:0xf bound_ctrl:1
	ds_write_b32 v162, v205 offset:896
	s_waitcnt lgkmcnt(4)
	v_pk_fma_f32 v[58:59], v[198:199], v[50:51], v[58:59] op_sel_hi:[0,1,1]
	v_pk_fma_f32 v[72:73], v[198:199], v[52:53], v[72:73] op_sel_hi:[0,1,1]
	v_pk_fma_f32 v[66:67], v[66:67], v[42:43], v[58:59]
	v_pk_fma_f32 v[64:65], v[64:65], v[44:45], v[72:73]
	v_pk_fma_f32 v[212:213], v[198:199], v[54:55], v[212:213] op_sel_hi:[0,1,1]
	v_pk_fma_f32 v[250:251], v[198:199], v[56:57], v[250:251] op_sel_hi:[0,1,1]
	v_pk_fma_f32 v[62:63], v[62:63], v[46:47], v[212:213]
	v_pk_fma_f32 v[60:61], v[60:61], v[48:49], v[250:251]
	ds_read_b128 v[50:53], v0 offset:22784
	ds_read_b128 v[54:57], v0 offset:22800
	ds_read_b128 v[42:45], v0 offset:6400
	ds_read_b128 v[46:49], v0 offset:6416
	v_pk_fma_f32 v[58:59], v[66:67], v[154:155], 0 op_sel_hi:[1,1,0]
	v_pk_fma_f32 v[72:73], v[64:65], v[156:157], 0 op_sel_hi:[1,1,0]
	v_pk_fma_f32 v[58:59], v[62:63], v[246:247], v[58:59]
	v_pk_fma_f32 v[72:73], v[60:61], v[248:249], v[72:73]
	ds_read_b128 v[154:157], v0 offset:2304
	ds_read_b128 v[246:249], v0 offset:2320
	v_pk_add_f32 v[58:59], v[58:59], v[72:73]
	ds_read_b128 v[34:37], v0 offset:18944
	ds_read_b128 v[38:41], v0 offset:18960
	s_waitcnt lgkmcnt(8)
	v_pk_mul_f32 v[200:201], v[66:67], v[200:201]
	v_pk_mul_f32 v[202:203], v[64:65], v[202:203]
	v_pk_fma_f32 v[200:201], v[62:63], v[230:231], v[200:201]
	v_pk_fma_f32 v[202:203], v[60:61], v[232:233], v[202:203]
	v_pk_add_f32 v[200:201], v[200:201], v[202:203]
	v_add_f32_e32 v207, v58, v59
	v_add_f32_e32 v198, v200, v201
	v_mov_b32_e32 v232, v159
	v_pk_mul_f32 v[58:59], v[68:69], v[232:233] op_sel_hi:[1,0]
	v_pk_mul_f32 v[72:73], v[70:71], v[232:233] op_sel_hi:[1,0]
	ds_read_b128 v[68:71], v0 offset:10752
	v_add_f32_dpp v198, v198, v198 quad_perm:[1,0,3,2] row_mask:0xf bank_mask:0xf bound_ctrl:1
	v_add_f32_dpp v207, v207, v207 quad_perm:[1,0,3,2] row_mask:0xf bank_mask:0xf bound_ctrl:1
	v_pk_mul_f32 v[212:213], v[150:151], v[232:233] op_sel_hi:[1,0]
	v_add_f32_dpp v198, v198, v198 quad_perm:[2,3,0,1] row_mask:0xf bank_mask:0xf bound_ctrl:1
	v_add_f32_dpp v207, v207, v207 quad_perm:[2,3,0,1] row_mask:0xf bank_mask:0xf bound_ctrl:1
	v_pk_mul_f32 v[250:251], v[152:153], v[232:233] op_sel_hi:[1,0]
	ds_read_b128 v[150:153], v0 offset:10768
	v_add_f32_dpp v198, v198, v198 row_half_mirror row_mask:0xf bank_mask:0xf bound_ctrl:1
	v_add_f32_dpp v163, v207, v207 row_half_mirror row_mask:0xf bank_mask:0xf bound_ctrl:1
	ds_read2st64_b32 v[158:159], v161 offset0:10 offset1:11
	ds_write_b32 v162, v163 offset:1024
	s_waitcnt lgkmcnt(5)
; DI float oct_sum(float v) { v += dpp_f<0xB1>(v); v += dpp_f<0x4E>(v); v += dpp_f<0x141>(v); return v; }
; DI void scan_item(const Params& p, int b, int h, int half, char* smem, unsigned* pgen, unsigned kp) {
;     ...
;       for (int s4 = 0; s4 < 4; ++s4) {
;         const int s = sg + s4;
;         const f32x2* a2 = (const f32x2*)(Al + s * 64 + cg * 8);
;         const f32x2* w2 = (const f32x2*)(Wl + s * 64 + cg * 8);
;         const f32x2* b2 = (const f32x2*)(Bl + s * 64 + cg * 8);
;         const f32x2* k2 = (const f32x2*)(Kl + s * 64 + cg * 8);
;         const f32x2* r2 = (const f32x2*)(Rl + s * 64 + cg * 8);
;         f32x2 o[20];
; #pragma unroll
;         for (int i = 0; i < 4; ++i) { o[i] = a2[i]; o[4 + i] = w2[i]; o[8 + i] = b2[i]; o[12 + i] = k2[i]; o[16 + i] = r2[i]; }
;         const float vr = Vl[s * 64 + 32 * half + rp];
;         f32x2 p0 = St[0] * o[0], p1 = St[1] * o[1];
;         p0 = __builtin_elementwise_fma(St[2], o[2], p0); p1 = __builtin_elementwise_fma(St[3], o[3], p1);
;         const float sa = oct_sum((p0.x + p0.y) + (p1.x + p1.y));
;         const f32x2 sv = {sa, sa}, vv = {vr, vr};
;         f32x2 y0 = {0.f, 0.f}, y1 = {0.f, 0.f};
; #pragma unroll
;         for (int i = 0; i < 4; i += 2) {
;           St[i] = __builtin_elementwise_fma(St[i], o[4 + i], __builtin_elementwise_fma(sv, o[8 + i], vv * o[12 + i]));
;           St[i + 1] = __builtin_elementwise_fma(St[i + 1], o[5 + i], __builtin_elementwise_fma(sv, o[9 + i], vv * o[13 + i]));
;           y0 = __builtin_elementwise_fma(St[i], o[16 + i], y0);
;           y1 = __builtin_elementwise_fma(St[i + 1], o[17 + i], y1);
;         }
;         yy[s4] = oct_sum((y0.x + y0.y) + (y1.x + y1.y));
;       }
;       if (cg == 0) {
; #pragma unroll
;         for (int s4 = 0; s4 < 4; ++s4) Yl[(sg + s4) * 32 + rp] = yy[s4];
	v_pk_fma_f32 v[58:59], v[198:199], v[50:51], v[58:59] op_sel_hi:[0,1,1]
	v_pk_fma_f32 v[72:73], v[198:199], v[52:53], v[72:73] op_sel_hi:[0,1,1]
	v_pk_fma_f32 v[66:67], v[66:67], v[42:43], v[58:59]
	v_pk_fma_f32 v[64:65], v[64:65], v[44:45], v[72:73]
	v_pk_fma_f32 v[212:213], v[198:199], v[54:55], v[212:213] op_sel_hi:[0,1,1]
	v_pk_fma_f32 v[250:251], v[198:199], v[56:57], v[250:251] op_sel_hi:[0,1,1]
	v_pk_fma_f32 v[62:63], v[62:63], v[46:47], v[212:213]
	v_pk_fma_f32 v[60:61], v[60:61], v[48:49], v[250:251]
	ds_read_b128 v[50:53], v0 offset:23040
	ds_read_b128 v[54:57], v0 offset:23056
	ds_read_b128 v[42:45], v0 offset:6656
	ds_read_b128 v[46:49], v0 offset:6672
	v_pk_fma_f32 v[58:59], v[66:67], v[154:155], 0 op_sel_hi:[1,1,0]
	v_pk_fma_f32 v[72:73], v[64:65], v[156:157], 0 op_sel_hi:[1,1,0]
	v_pk_fma_f32 v[58:59], v[62:63], v[246:247], v[58:59]
	v_pk_fma_f32 v[72:73], v[60:61], v[248:249], v[72:73]
	ds_read_b128 v[154:157], v0 offset:2560
	ds_read_b128 v[246:249], v0 offset:2576
	v_pk_add_f32 v[58:59], v[58:59], v[72:73]
	ds_read_b128 v[200:203], v0 offset:19200
	ds_read_b128 v[230:233], v0 offset:19216
	s_waitcnt lgkmcnt(8)
	v_pk_mul_f32 v[34:35], v[66:67], v[34:35]
	v_pk_mul_f32 v[36:37], v[64:65], v[36:37]
	v_pk_fma_f32 v[34:35], v[62:63], v[38:39], v[34:35]
	v_pk_fma_f32 v[36:37], v[60:61], v[40:41], v[36:37]
	v_pk_add_f32 v[34:35], v[34:35], v[36:37]
	v_add_f32_e32 v207, v58, v59
	v_add_f32_e32 v198, v34, v35
	v_pk_mul_f32 v[58:59], v[68:69], v[158:159] op_sel_hi:[1,0]
	v_pk_mul_f32 v[72:73], v[70:71], v[158:159] op_sel_hi:[1,0]
	ds_read_b128 v[68:71], v0 offset:11008
	v_add_f32_dpp v198, v198, v198 quad_perm:[1,0,3,2] row_mask:0xf bank_mask:0xf bound_ctrl:1
	v_add_f32_dpp v207, v207, v207 quad_perm:[1,0,3,2] row_mask:0xf bank_mask:0xf bound_ctrl:1
	v_pk_mul_f32 v[212:213], v[150:151], v[158:159] op_sel_hi:[1,0]
	v_add_f32_dpp v198, v198, v198 quad_perm:[2,3,0,1] row_mask:0xf bank_mask:0xf bound_ctrl:1
	v_add_f32_dpp v207, v207, v207 quad_perm:[2,3,0,1] row_mask:0xf bank_mask:0xf bound_ctrl:1
	v_pk_mul_f32 v[250:251], v[152:153], v[158:159] op_sel_hi:[1,0]
	ds_read_b128 v[150:153], v0 offset:11024
	v_add_f32_dpp v198, v198, v198 row_half_mirror row_mask:0xf bank_mask:0xf bound_ctrl:1
	v_add_f32_dpp v205, v207, v207 row_half_mirror row_mask:0xf bank_mask:0xf bound_ctrl:1
	ds_write_b32 v162, v205 offset:1152
	s_waitcnt lgkmcnt(4)
	v_pk_fma_f32 v[58:59], v[198:199], v[50:51], v[58:59] op_sel_hi:[0,1,1]
	v_pk_fma_f32 v[72:73], v[198:199], v[52:53], v[72:73] op_sel_hi:[0,1,1]
	v_pk_fma_f32 v[66:67], v[66:67], v[42:43], v[58:59]
	v_pk_fma_f32 v[64:65], v[64:65], v[44:45], v[72:73]
	v_pk_fma_f32 v[212:213], v[198:199], v[54:55], v[212:213] op_sel_hi:[0,1,1]
	v_pk_fma_f32 v[250:251], v[198:199], v[56:57], v[250:251] op_sel_hi:[0,1,1]
	v_pk_fma_f32 v[62:63], v[62:63], v[46:47], v[212:213]
	v_pk_fma_f32 v[60:61], v[60:61], v[48:49], v[250:251]
	ds_read_b128 v[50:53], v0 offset:23296
	ds_read_b128 v[54:57], v0 offset:23312
	ds_read_b128 v[42:45], v0 offset:6912
	ds_read_b128 v[46:49], v0 offset:6928
	v_pk_fma_f32 v[58:59], v[66:67], v[154:155], 0 op_sel_hi:[1,1,0]
	v_pk_fma_f32 v[72:73], v[64:65], v[156:157], 0 op_sel_hi:[1,1,0]
	v_pk_fma_f32 v[58:59], v[62:63], v[246:247], v[58:59]
	v_pk_fma_f32 v[72:73], v[60:61], v[248:249], v[72:73]
	ds_read_b128 v[154:157], v0 offset:2816
	ds_read_b128 v[246:249], v0 offset:2832
	v_pk_add_f32 v[58:59], v[58:59], v[72:73]
	ds_read_b128 v[34:37], v0 offset:19456
	ds_read_b128 v[38:41], v0 offset:19472
	s_waitcnt lgkmcnt(8)
	v_pk_mul_f32 v[200:201], v[66:67], v[200:201]
	v_pk_mul_f32 v[202:203], v[64:65], v[202:203]
	v_pk_fma_f32 v[200:201], v[62:63], v[230:231], v[200:201]
	v_pk_fma_f32 v[202:203], v[60:61], v[232:233], v[202:203]
	v_pk_add_f32 v[200:201], v[200:201], v[202:203]
	v_add_f32_e32 v207, v58, v59
	v_add_f32_e32 v198, v200, v201
	v_mov_b32_e32 v232, v159
	v_pk_mul_f32 v[58:59], v[68:69], v[232:233] op_sel_hi:[1,0]
	v_pk_mul_f32 v[72:73], v[70:71], v[232:233] op_sel_hi:[1,0]
	ds_read_b128 v[68:71], v0 offset:11264
	v_add_f32_dpp v198, v198, v198 quad_perm:[1,0,3,2] row_mask:0xf bank_mask:0xf bound_ctrl:1
	v_add_f32_dpp v207, v207, v207 quad_perm:[1,0,3,2] row_mask:0xf bank_mask:0xf bound_ctrl:1
	v_pk_mul_f32 v[212:213], v[150:151], v[232:233] op_sel_hi:[1,0]
	v_add_f32_dpp v198, v198, v198 quad_perm:[2,3,0,1] row_mask:0xf bank_mask:0xf bound_ctrl:1
	v_add_f32_dpp v207, v207, v207 quad_perm:[2,3,0,1] row_mask:0xf bank_mask:0xf bound_ctrl:1
	v_pk_mul_f32 v[250:251], v[152:153], v[232:233] op_sel_hi:[1,0]
	ds_read_b128 v[150:153], v0 offset:11280
	v_add_f32_dpp v198, v198, v198 row_half_mirror row_mask:0xf bank_mask:0xf bound_ctrl:1
	v_add_f32_dpp v163, v207, v207 row_half_mirror row_mask:0xf bank_mask:0xf bound_ctrl:1
	ds_read2st64_b32 v[158:159], v161 offset0:12 offset1:13
	ds_write_b32 v162, v163 offset:1280
	s_waitcnt lgkmcnt(5)
	v_pk_fma_f32 v[58:59], v[198:199], v[50:51], v[58:59] op_sel_hi:[0,1,1]
	v_pk_fma_f32 v[72:73], v[198:199], v[52:53], v[72:73] op_sel_hi:[0,1,1]
	v_pk_fma_f32 v[66:67], v[66:67], v[42:43], v[58:59]
	v_pk_fma_f32 v[64:65], v[64:65], v[44:45], v[72:73]
	v_pk_fma_f32 v[212:213], v[198:199], v[54:55], v[212:213] op_sel_hi:[0,1,1]
	v_pk_fma_f32 v[250:251], v[198:199], v[56:57], v[250:251] op_sel_hi:[0,1,1]
	v_pk_fma_f32 v[62:63], v[62:63], v[46:47], v[212:213]
	v_pk_fma_f32 v[60:61], v[60:61], v[48:49], v[250:251]
	ds_read_b128 v[50:53], v0 offset:23552
	ds_read_b128 v[54:57], v0 offset:23568
	ds_read_b128 v[42:45], v0 offset:7168
	ds_read_b128 v[46:49], v0 offset:7184
	v_pk_fma_f32 v[58:59], v[66:67], v[154:155], 0 op_sel_hi:[1,1,0]
	v_pk_fma_f32 v[72:73], v[64:65], v[156:157], 0 op_sel_hi:[1,1,0]
	v_pk_fma_f32 v[58:59], v[62:63], v[246:247], v[58:59]
	v_pk_fma_f32 v[72:73], v[60:61], v[248:249], v[72:73]
	ds_read_b128 v[154:157], v0 offset:3072
	ds_read_b128 v[246:249], v0 offset:3088
	v_pk_add_f32 v[58:59], v[58:59], v[72:73]
	ds_read_b128 v[200:203], v0 offset:19712
	ds_read_b128 v[230:233], v0 offset:19728
	s_waitcnt lgkmcnt(8)
; DI float oct_sum(float v) { v += dpp_f<0xB1>(v); v += dpp_f<0x4E>(v); v += dpp_f<0x141>(v); return v; }
; DI void scan_item(const Params& p, int b, int h, int half, char* smem, unsigned* pgen, unsigned kp) {
;     ...
;       for (int s4 = 0; s4 < 4; ++s4) {
;         const int s = sg + s4;
;         const f32x2* a2 = (const f32x2*)(Al + s * 64 + cg * 8);
;         const f32x2* w2 = (const f32x2*)(Wl + s * 64 + cg * 8);
;         const f32x2* b2 = (const f32x2*)(Bl + s * 64 + cg * 8);
;         const f32x2* k2 = (const f32x2*)(Kl + s * 64 + cg * 8);
;         const f32x2* r2 = (const f32x2*)(Rl + s * 64 + cg * 8);
;         f32x2 o[20];
; #pragma unroll
;         for (int i = 0; i < 4; ++i) { o[i] = a2[i]; o[4 + i] = w2[i]; o[8 + i] = b2[i]; o[12 + i] = k2[i]; o[16 + i] = r2[i]; }
;         const float vr = Vl[s * 64 + 32 * half + rp];
;         f32x2 p0 = St[0] * o[0], p1 = St[1] * o[1];
;         p0 = __builtin_elementwise_fma(St[2], o[2], p0); p1 = __builtin_elementwise_fma(St[3], o[3], p1);
;         const float sa = oct_sum((p0.x + p0.y) + (p1.x + p1.y));
;         const f32x2 sv = {sa, sa}, vv = {vr, vr};
;         f32x2 y0 = {0.f, 0.f}, y1 = {0.f, 0.f};
; #pragma unroll
;         for (int i = 0; i < 4; i += 2) {
;           St[i] = __builtin_elementwise_fma(St[i], o[4 + i], __builtin_elementwise_fma(sv, o[8 + i], vv * o[12 + i]));
;           St[i + 1] = __builtin_elementwise_fma(St[i + 1], o[5 + i], __builtin_elementwise_fma(sv, o[9 + i], vv * o[13 + i]));
;           y0 = __builtin_elementwise_fma(St[i], o[16 + i], y0);
;           y1 = __builtin_elementwise_fma(St[i + 1], o[17 + i], y1);
;         }
;         yy[s4] = oct_sum((y0.x + y0.y) + (y1.x + y1.y));
;       }
;       if (cg == 0) {
; #pragma unroll
;         for (int s4 = 0; s4 < 4; ++s4) Yl[(sg + s4) * 32 + rp] = yy[s4];
	v_pk_mul_f32 v[34:35], v[66:67], v[34:35]
	v_pk_mul_f32 v[36:37], v[64:65], v[36:37]
	v_pk_fma_f32 v[34:35], v[62:63], v[38:39], v[34:35]
	v_pk_fma_f32 v[36:37], v[60:61], v[40:41], v[36:37]
	v_pk_add_f32 v[34:35], v[34:35], v[36:37]
	v_add_f32_e32 v207, v58, v59
	v_add_f32_e32 v198, v34, v35
	v_pk_mul_f32 v[58:59], v[68:69], v[158:159] op_sel_hi:[1,0]
	v_pk_mul_f32 v[72:73], v[70:71], v[158:159] op_sel_hi:[1,0]
	ds_read_b128 v[68:71], v0 offset:11520
	v_add_f32_dpp v198, v198, v198 quad_perm:[1,0,3,2] row_mask:0xf bank_mask:0xf bound_ctrl:1
	v_add_f32_dpp v207, v207, v207 quad_perm:[1,0,3,2] row_mask:0xf bank_mask:0xf bound_ctrl:1
	v_pk_mul_f32 v[212:213], v[150:151], v[158:159] op_sel_hi:[1,0]
	v_add_f32_dpp v198, v198, v198 quad_perm:[2,3,0,1] row_mask:0xf bank_mask:0xf bound_ctrl:1
	v_add_f32_dpp v207, v207, v207 quad_perm:[2,3,0,1] row_mask:0xf bank_mask:0xf bound_ctrl:1
	v_pk_mul_f32 v[250:251], v[152:153], v[158:159] op_sel_hi:[1,0]
	ds_read_b128 v[150:153], v0 offset:11536
	v_add_f32_dpp v198, v198, v198 row_half_mirror row_mask:0xf bank_mask:0xf bound_ctrl:1
	v_add_f32_dpp v205, v207, v207 row_half_mirror row_mask:0xf bank_mask:0xf bound_ctrl:1
	ds_write_b32 v162, v205 offset:1408
	s_waitcnt lgkmcnt(4)
	v_pk_fma_f32 v[58:59], v[198:199], v[50:51], v[58:59] op_sel_hi:[0,1,1]
	v_pk_fma_f32 v[72:73], v[198:199], v[52:53], v[72:73] op_sel_hi:[0,1,1]
	v_pk_fma_f32 v[66:67], v[66:67], v[42:43], v[58:59]
	v_pk_fma_f32 v[64:65], v[64:65], v[44:45], v[72:73]
	v_pk_fma_f32 v[212:213], v[198:199], v[54:55], v[212:213] op_sel_hi:[0,1,1]
	v_pk_fma_f32 v[250:251], v[198:199], v[56:57], v[250:251] op_sel_hi:[0,1,1]
	v_pk_fma_f32 v[62:63], v[62:63], v[46:47], v[212:213]
	v_pk_fma_f32 v[60:61], v[60:61], v[48:49], v[250:251]
	ds_read_b128 v[50:53], v0 offset:23808
	ds_read_b128 v[54:57], v0 offset:23824
	ds_read_b128 v[42:45], v0 offset:7424
	ds_read_b128 v[46:49], v0 offset:7440
	v_pk_fma_f32 v[58:59], v[66:67], v[154:155], 0 op_sel_hi:[1,1,0]
	v_pk_fma_f32 v[72:73], v[64:65], v[156:157], 0 op_sel_hi:[1,1,0]
	v_pk_fma_f32 v[58:59], v[62:63], v[246:247], v[58:59]
	v_pk_fma_f32 v[72:73], v[60:61], v[248:249], v[72:73]
	ds_read_b128 v[154:157], v0 offset:3328
	ds_read_b128 v[246:249], v0 offset:3344
	v_pk_add_f32 v[58:59], v[58:59], v[72:73]
	ds_read_b128 v[34:37], v0 offset:19968
	ds_read_b128 v[38:41], v0 offset:19984
	s_waitcnt lgkmcnt(8)
	v_pk_mul_f32 v[200:201], v[66:67], v[200:201]
	v_pk_mul_f32 v[202:203], v[64:65], v[202:203]
	v_pk_fma_f32 v[200:201], v[62:63], v[230:231], v[200:201]
	v_pk_fma_f32 v[202:203], v[60:61], v[232:233], v[202:203]
	v_pk_add_f32 v[200:201], v[200:201], v[202:203]
	v_add_f32_e32 v207, v58, v59
	v_add_f32_e32 v198, v200, v201
	v_mov_b32_e32 v232, v159
	v_pk_mul_f32 v[58:59], v[68:69], v[232:233] op_sel_hi:[1,0]
	v_pk_mul_f32 v[72:73], v[70:71], v[232:233] op_sel_hi:[1,0]
	ds_read_b128 v[68:71], v0 offset:11776
	v_add_f32_dpp v198, v198, v198 quad_perm:[1,0,3,2] row_mask:0xf bank_mask:0xf bound_ctrl:1
	v_add_f32_dpp v207, v207, v207 quad_perm:[1,0,3,2] row_mask:0xf bank_mask:0xf bound_ctrl:1
	v_pk_mul_f32 v[212:213], v[150:151], v[232:233] op_sel_hi:[1,0]
	v_add_f32_dpp v198, v198, v198 quad_perm:[2,3,0,1] row_mask:0xf bank_mask:0xf bound_ctrl:1
	v_add_f32_dpp v207, v207, v207 quad_perm:[2,3,0,1] row_mask:0xf bank_mask:0xf bound_ctrl:1
	v_pk_mul_f32 v[250:251], v[152:153], v[232:233] op_sel_hi:[1,0]
	ds_read_b128 v[150:153], v0 offset:11792
	v_add_f32_dpp v198, v198, v198 row_half_mirror row_mask:0xf bank_mask:0xf bound_ctrl:1
	v_add_f32_dpp v163, v207, v207 row_half_mirror row_mask:0xf bank_mask:0xf bound_ctrl:1
	ds_read2st64_b32 v[158:159], v161 offset0:14 offset1:15
	ds_write_b32 v162, v163 offset:1536
	s_waitcnt lgkmcnt(5)
	v_pk_fma_f32 v[58:59], v[198:199], v[50:51], v[58:59] op_sel_hi:[0,1,1]
	v_pk_fma_f32 v[72:73], v[198:199], v[52:53], v[72:73] op_sel_hi:[0,1,1]
	v_pk_fma_f32 v[66:67], v[66:67], v[42:43], v[58:59]
	v_pk_fma_f32 v[64:65], v[64:65], v[44:45], v[72:73]
	v_pk_fma_f32 v[212:213], v[198:199], v[54:55], v[212:213] op_sel_hi:[0,1,1]
	v_pk_fma_f32 v[250:251], v[198:199], v[56:57], v[250:251] op_sel_hi:[0,1,1]
	v_pk_fma_f32 v[62:63], v[62:63], v[46:47], v[212:213]
	v_pk_fma_f32 v[60:61], v[60:61], v[48:49], v[250:251]
	ds_read_b128 v[50:53], v0 offset:24064
	ds_read_b128 v[54:57], v0 offset:24080
	ds_read_b128 v[42:45], v0 offset:7680
	ds_read_b128 v[46:49], v0 offset:7696
	v_pk_fma_f32 v[58:59], v[66:67], v[154:155], 0 op_sel_hi:[1,1,0]
	v_pk_fma_f32 v[72:73], v[64:65], v[156:157], 0 op_sel_hi:[1,1,0]
	v_pk_fma_f32 v[58:59], v[62:63], v[246:247], v[58:59]
	v_pk_fma_f32 v[72:73], v[60:61], v[248:249], v[72:73]
	ds_read_b128 v[154:157], v0 offset:3584
	ds_read_b128 v[246:249], v0 offset:3600
	v_pk_add_f32 v[58:59], v[58:59], v[72:73]
	ds_read_b128 v[200:203], v0 offset:20224
	ds_read_b128 v[230:233], v0 offset:20240
	s_waitcnt lgkmcnt(8)
; DI float oct_sum(float v) { v += dpp_f<0xB1>(v); v += dpp_f<0x4E>(v); v += dpp_f<0x141>(v); return v; }
; DI void scan_item(const Params& p, int b, int h, int half, char* smem, unsigned* pgen, unsigned kp) {
;     ...
;       for (int s4 = 0; s4 < 4; ++s4) {
;         const int s = sg + s4;
;         const f32x2* a2 = (const f32x2*)(Al + s * 64 + cg * 8);
;         const f32x2* w2 = (const f32x2*)(Wl + s * 64 + cg * 8);
;         const f32x2* b2 = (const f32x2*)(Bl + s * 64 + cg * 8);
;         const f32x2* k2 = (const f32x2*)(Kl + s * 64 + cg * 8);
;         const f32x2* r2 = (const f32x2*)(Rl + s * 64 + cg * 8);
;         f32x2 o[20];
; #pragma unroll
;         for (int i = 0; i < 4; ++i) { o[i] = a2[i]; o[4 + i] = w2[i]; o[8 + i] = b2[i]; o[12 + i] = k2[i]; o[16 + i] = r2[i]; }
;         const float vr = Vl[s * 64 + 32 * half + rp];
;         f32x2 p0 = St[0] * o[0], p1 = St[1] * o[1];
;         p0 = __builtin_elementwise_fma(St[2], o[2], p0); p1 = __builtin_elementwise_fma(St[3], o[3], p1);
;         const float sa = oct_sum((p0.x + p0.y) + (p1.x + p1.y));
;         const f32x2 sv = {sa, sa}, vv = {vr, vr};
;         f32x2 y0 = {0.f, 0.f}, y1 = {0.f, 0.f};
; #pragma unroll
;         for (int i = 0; i < 4; i += 2) {
;           St[i] = __builtin_elementwise_fma(St[i], o[4 + i], __builtin_elementwise_fma(sv, o[8 + i], vv * o[12 + i]));
;           St[i + 1] = __builtin_elementwise_fma(St[i + 1], o[5 + i], __builtin_elementwise_fma(sv, o[9 + i], vv * o[13 + i]));
;           y0 = __builtin_elementwise_fma(St[i], o[16 + i], y0);
;           y1 = __builtin_elementwise_fma(St[i + 1], o[17 + i], y1);
;         }
;         yy[s4] = oct_sum((y0.x + y0.y) + (y1.x + y1.y));
;       }
;       if (cg == 0) {
; #pragma unroll
;         for (int s4 = 0; s4 < 4; ++s4) Yl[(sg + s4) * 32 + rp] = yy[s4];
	v_pk_mul_f32 v[34:35], v[66:67], v[34:35]
	v_pk_mul_f32 v[36:37], v[64:65], v[36:37]
	v_pk_fma_f32 v[34:35], v[62:63], v[38:39], v[34:35]
	v_pk_fma_f32 v[36:37], v[60:61], v[40:41], v[36:37]
	v_pk_add_f32 v[34:35], v[34:35], v[36:37]
	v_add_f32_e32 v207, v58, v59
	v_add_f32_e32 v198, v34, v35
	v_pk_mul_f32 v[58:59], v[68:69], v[158:159] op_sel_hi:[1,0]
	v_pk_mul_f32 v[72:73], v[70:71], v[158:159] op_sel_hi:[1,0]
	ds_read_b128 v[68:71], v0 offset:12032
	v_add_f32_dpp v198, v198, v198 quad_perm:[1,0,3,2] row_mask:0xf bank_mask:0xf bound_ctrl:1
	v_add_f32_dpp v207, v207, v207 quad_perm:[1,0,3,2] row_mask:0xf bank_mask:0xf bound_ctrl:1
	v_pk_mul_f32 v[212:213], v[150:151], v[158:159] op_sel_hi:[1,0]
	v_add_f32_dpp v198, v198, v198 quad_perm:[2,3,0,1] row_mask:0xf bank_mask:0xf bound_ctrl:1
	v_add_f32_dpp v207, v207, v207 quad_perm:[2,3,0,1] row_mask:0xf bank_mask:0xf bound_ctrl:1
	v_pk_mul_f32 v[250:251], v[152:153], v[158:159] op_sel_hi:[1,0]
	ds_read_b128 v[150:153], v0 offset:12048
	v_add_f32_dpp v198, v198, v198 row_half_mirror row_mask:0xf bank_mask:0xf bound_ctrl:1
	v_add_f32_dpp v205, v207, v207 row_half_mirror row_mask:0xf bank_mask:0xf bound_ctrl:1
	ds_write_b32 v162, v205 offset:1664
	s_waitcnt lgkmcnt(4)
	v_pk_fma_f32 v[58:59], v[198:199], v[50:51], v[58:59] op_sel_hi:[0,1,1]
	v_pk_fma_f32 v[72:73], v[198:199], v[52:53], v[72:73] op_sel_hi:[0,1,1]
	v_pk_fma_f32 v[66:67], v[66:67], v[42:43], v[58:59]
	v_pk_fma_f32 v[64:65], v[64:65], v[44:45], v[72:73]
	v_pk_fma_f32 v[212:213], v[198:199], v[54:55], v[212:213] op_sel_hi:[0,1,1]
	v_pk_fma_f32 v[250:251], v[198:199], v[56:57], v[250:251] op_sel_hi:[0,1,1]
	v_pk_fma_f32 v[62:63], v[62:63], v[46:47], v[212:213]
	v_pk_fma_f32 v[60:61], v[60:61], v[48:49], v[250:251]
	ds_read_b128 v[50:53], v0 offset:24320
	ds_read_b128 v[54:57], v0 offset:24336
	ds_read_b128 v[42:45], v0 offset:7936
	ds_read_b128 v[46:49], v0 offset:7952
	v_pk_fma_f32 v[58:59], v[66:67], v[154:155], 0 op_sel_hi:[1,1,0]
	v_pk_fma_f32 v[72:73], v[64:65], v[156:157], 0 op_sel_hi:[1,1,0]
	v_pk_fma_f32 v[58:59], v[62:63], v[246:247], v[58:59]
	v_pk_fma_f32 v[72:73], v[60:61], v[248:249], v[72:73]
	ds_read_b128 v[154:157], v0 offset:3840
	ds_read_b128 v[246:249], v0 offset:3856
	v_pk_add_f32 v[58:59], v[58:59], v[72:73]
	s_waitcnt lgkmcnt(6)
	v_pk_mul_f32 v[200:201], v[66:67], v[200:201]
	v_pk_mul_f32 v[202:203], v[64:65], v[202:203]
	v_pk_fma_f32 v[200:201], v[62:63], v[230:231], v[200:201]
	v_pk_fma_f32 v[202:203], v[60:61], v[232:233], v[202:203]
	v_pk_add_f32 v[200:201], v[200:201], v[202:203]
	v_add_f32_e32 v207, v58, v59
	v_add_f32_e32 v198, v200, v201
	v_mov_b32_e32 v232, v159
	v_pk_mul_f32 v[58:59], v[68:69], v[232:233] op_sel_hi:[1,0]
	v_pk_mul_f32 v[72:73], v[70:71], v[232:233] op_sel_hi:[1,0]
	v_add_f32_dpp v198, v198, v198 quad_perm:[1,0,3,2] row_mask:0xf bank_mask:0xf bound_ctrl:1
	v_add_f32_dpp v207, v207, v207 quad_perm:[1,0,3,2] row_mask:0xf bank_mask:0xf bound_ctrl:1
	v_pk_mul_f32 v[212:213], v[150:151], v[232:233] op_sel_hi:[1,0]
	v_add_f32_dpp v198, v198, v198 quad_perm:[2,3,0,1] row_mask:0xf bank_mask:0xf bound_ctrl:1
	v_add_f32_dpp v207, v207, v207 quad_perm:[2,3,0,1] row_mask:0xf bank_mask:0xf bound_ctrl:1
	v_pk_mul_f32 v[250:251], v[152:153], v[232:233] op_sel_hi:[1,0]
	v_add_f32_dpp v198, v198, v198 row_half_mirror row_mask:0xf bank_mask:0xf bound_ctrl:1
	v_add_f32_dpp v163, v207, v207 row_half_mirror row_mask:0xf bank_mask:0xf bound_ctrl:1
	ds_write_b32 v162, v163 offset:1792
	s_waitcnt lgkmcnt(0)
	v_pk_fma_f32 v[58:59], v[198:199], v[50:51], v[58:59] op_sel_hi:[0,1,1]
	v_pk_fma_f32 v[72:73], v[198:199], v[52:53], v[72:73] op_sel_hi:[0,1,1]
	v_pk_fma_f32 v[66:67], v[66:67], v[42:43], v[58:59]
	v_pk_fma_f32 v[64:65], v[64:65], v[44:45], v[72:73]
	v_pk_fma_f32 v[212:213], v[198:199], v[54:55], v[212:213] op_sel_hi:[0,1,1]
	v_pk_fma_f32 v[250:251], v[198:199], v[56:57], v[250:251] op_sel_hi:[0,1,1]
	v_pk_fma_f32 v[62:63], v[62:63], v[46:47], v[212:213]
	v_pk_fma_f32 v[60:61], v[60:61], v[48:49], v[250:251]
	v_pk_fma_f32 v[58:59], v[66:67], v[154:155], 0 op_sel_hi:[1,1,0]
	v_pk_fma_f32 v[72:73], v[64:65], v[156:157], 0 op_sel_hi:[1,1,0]
	v_pk_fma_f32 v[58:59], v[62:63], v[246:247], v[58:59]
	v_pk_fma_f32 v[72:73], v[60:61], v[248:249], v[72:73]
	v_pk_add_f32 v[58:59], v[58:59], v[72:73]
	s_nop 0
	v_add_f32_e32 v207, v58, v59
	s_nop 1
	v_add_f32_dpp v207, v207, v207 quad_perm:[1,0,3,2] row_mask:0xf bank_mask:0xf bound_ctrl:1
	s_nop 1
	v_add_f32_dpp v207, v207, v207 quad_perm:[2,3,0,1] row_mask:0xf bank_mask:0xf bound_ctrl:1
	s_nop 1
	v_add_f32_dpp v205, v207, v207 row_half_mirror row_mask:0xf bank_mask:0xf bound_ctrl:1
	ds_write_b32 v162, v205 offset:1920

; DI float oct_sum(float v) { v += dpp_f<0xB1>(v); v += dpp_f<0x4E>(v); v += dpp_f<0x141>(v); return v; }
; DI void scan_item(const Params& p, int b, int h, int half, char* smem, unsigned* pgen, unsigned kp) {
;     ...
;     for (int sg = 0; sg < SC; sg += 4) {
;       float yy[4];
; #pragma unroll
;       for (int s4 = 0; s4 < 4; ++s4) {
;         const int s = sg + s4;
;         const f32x2* a2 = (const f32x2*)(Al + s * 64 + cg * 8);
;         const f32x2* w2 = (const f32x2*)(Wl + s * 64 + cg * 8);
;         const f32x2* b2 = (const f32x2*)(Bl + s * 64 + cg * 8);
;         const f32x2* k2 = (const f32x2*)(Kl + s * 64 + cg * 8);
;         const f32x2* r2 = (const f32x2*)(Rl + s * 64 + cg * 8);
;         f32x2 o[20];
; #pragma unroll
;         for (int i = 0; i < 4; ++i) { o[i] = a2[i]; o[4 + i] = w2[i]; o[8 + i] = b2[i]; o[12 + i] = k2[i]; o[16 + i] = r2[i]; }
;         const float vr = Vl[s * 64 + 32 * half + rp];
;         f32x2 p0 = St[0] * o[0], p1 = St[1] * o[1];
;         p0 = __builtin_elementwise_fma(St[2], o[2], p0); p1 = __builtin_elementwise_fma(St[3], o[3], p1);
;         const float sa = oct_sum((p0.x + p0.y) + (p1.x + p1.y));
;         const f32x2 sv = {sa, sa}, vv = {vr, vr};
;         f32x2 y0 = {0.f, 0.f}, y1 = {0.f, 0.f};
; #pragma unroll
;         for (int i = 0; i < 4; i += 2) {
;           St[i] = __builtin_elementwise_fma(St[i], o[4 + i], __builtin_elementwise_fma(sv, o[8 + i], vv * o[12 + i]));
;           St[i + 1] = __builtin_elementwise_fma(St[i + 1], o[5 + i], __builtin_elementwise_fma(sv, o[9 + i], vv * o[13 + i]));
;           y0 = __builtin_elementwise_fma(St[i], o[16 + i], y0);
;           y1 = __builtin_elementwise_fma(St[i + 1], o[17 + i], y1);
;         }
;         yy[s4] = oct_sum((y0.x + y0.y) + (y1.x + y1.y));
;       }
;       if (cg == 0) {
; #pragma unroll
;         for (int s4 = 0; s4 < 4; ++s4) Yl[(sg + s4) * 32 + rp] = yy[s4];
.LBB0_711:
	s_mov_b32 s18, -4
	v_mov_b32_e32 v0, v214
	v_mov_b32_e32 v161, v160
	v_lshlrev_b32_e32 v162, 2, v173
	v_add_u32_e32 v162, 0xb000, v162
	v_cndmask_b32_e64 v162, v162, v225, s[12:13]
	ds_read_b128 v[34:37], v0 offset:16384
	ds_read_b128 v[38:41], v0 offset:16400
	ds_read_b128 v[68:71], v0 offset:8192
	ds_read_b128 v[150:153], v0 offset:8208
	ds_read2st64_b32 v[158:159], v161 offset0:0 offset1:1
	ds_read_b128 v[50:53], v0 offset:20480
	ds_read_b128 v[54:57], v0 offset:20496
	ds_read_b128 v[42:45], v0 offset:4096
	ds_read_b128 v[46:49], v0 offset:4112
	ds_read_b128 v[154:157], v0 offset:0
	ds_read_b128 v[246:249], v0 offset:16
	ds_read_b128 v[200:203], v0 offset:16640
	ds_read_b128 v[230:233], v0 offset:16656
	s_waitcnt lgkmcnt(8)
	v_pk_mul_f32 v[34:35], v[66:67], v[34:35]
	v_pk_mul_f32 v[36:37], v[64:65], v[36:37]
	v_pk_fma_f32 v[34:35], v[62:63], v[38:39], v[34:35]
	v_pk_fma_f32 v[36:37], v[60:61], v[40:41], v[36:37]
	v_pk_add_f32 v[34:35], v[34:35], v[36:37]
	v_add_f32_e32 v198, v34, v35
	v_pk_mul_f32 v[58:59], v[68:69], v[158:159] op_sel_hi:[1,0]
	v_pk_mul_f32 v[72:73], v[70:71], v[158:159] op_sel_hi:[1,0]
	ds_read_b128 v[68:71], v0 offset:8448
	v_add_f32_dpp v198, v198, v198 quad_perm:[1,0,3,2] row_mask:0xf bank_mask:0xf bound_ctrl:1
	s_nop 0
	v_pk_mul_f32 v[212:213], v[150:151], v[158:159] op_sel_hi:[1,0]
	v_add_f32_dpp v198, v198, v198 quad_perm:[2,3,0,1] row_mask:0xf bank_mask:0xf bound_ctrl:1
	s_nop 0
	v_pk_mul_f32 v[250:251], v[152:153], v[158:159] op_sel_hi:[1,0]
	ds_read_b128 v[150:153], v0 offset:8464
	v_add_f32_dpp v198, v198, v198 row_half_mirror row_mask:0xf bank_mask:0xf bound_ctrl:1
	s_waitcnt lgkmcnt(4)
	v_pk_fma_f32 v[58:59], v[198:199], v[50:51], v[58:59] op_sel_hi:[0,1,1]
	v_pk_fma_f32 v[72:73], v[198:199], v[52:53], v[72:73] op_sel_hi:[0,1,1]
	v_pk_fma_f32 v[66:67], v[66:67], v[42:43], v[58:59]
	v_pk_fma_f32 v[64:65], v[64:65], v[44:45], v[72:73]
	v_pk_fma_f32 v[212:213], v[198:199], v[54:55], v[212:213] op_sel_hi:[0,1,1]
	v_pk_fma_f32 v[250:251], v[198:199], v[56:57], v[250:251] op_sel_hi:[0,1,1]
	v_pk_fma_f32 v[62:63], v[62:63], v[46:47], v[212:213]
	v_pk_fma_f32 v[60:61], v[60:61], v[48:49], v[250:251]
	ds_read_b128 v[50:53], v0 offset:20736
	ds_read_b128 v[54:57], v0 offset:20752
	ds_read_b128 v[42:45], v0 offset:4352
	ds_read_b128 v[46:49], v0 offset:4368
	v_pk_fma_f32 v[58:59], v[66:67], v[154:155], 0 op_sel_hi:[1,1,0]
	v_pk_fma_f32 v[72:73], v[64:65], v[156:157], 0 op_sel_hi:[1,1,0]
	v_pk_fma_f32 v[58:59], v[62:63], v[246:247], v[58:59]
	v_pk_fma_f32 v[72:73], v[60:61], v[248:249], v[72:73]
	ds_read_b128 v[154:157], v0 offset:256
	ds_read_b128 v[246:249], v0 offset:272
	v_pk_add_f32 v[58:59], v[58:59], v[72:73]
	ds_read_b128 v[34:37], v0 offset:16896
	ds_read_b128 v[38:41], v0 offset:16912
	s_waitcnt lgkmcnt(8)
	v_pk_mul_f32 v[200:201], v[66:67], v[200:201]
	v_pk_mul_f32 v[202:203], v[64:65], v[202:203]
	v_pk_fma_f32 v[200:201], v[62:63], v[230:231], v[200:201]
	v_pk_fma_f32 v[202:203], v[60:61], v[232:233], v[202:203]
	v_pk_add_f32 v[200:201], v[200:201], v[202:203]
	v_add_f32_e32 v207, v58, v59
	v_add_f32_e32 v198, v200, v201
	v_mov_b32_e32 v232, v159
	v_pk_mul_f32 v[58:59], v[68:69], v[232:233] op_sel_hi:[1,0]
	v_pk_mul_f32 v[72:73], v[70:71], v[232:233] op_sel_hi:[1,0]
	ds_read_b128 v[68:71], v0 offset:8704
	v_add_f32_dpp v198, v198, v198 quad_perm:[1,0,3,2] row_mask:0xf bank_mask:0xf bound_ctrl:1
	v_add_f32_dpp v207, v207, v207 quad_perm:[1,0,3,2] row_mask:0xf bank_mask:0xf bound_ctrl:1
	v_pk_mul_f32 v[212:213], v[150:151], v[232:233] op_sel_hi:[1,0]
	v_add_f32_dpp v198, v198, v198 quad_perm:[2,3,0,1] row_mask:0xf bank_mask:0xf bound_ctrl:1
	v_add_f32_dpp v207, v207, v207 quad_perm:[2,3,0,1] row_mask:0xf bank_mask:0xf bound_ctrl:1
	v_pk_mul_f32 v[250:251], v[152:153], v[232:233] op_sel_hi:[1,0]
	ds_read_b128 v[150:153], v0 offset:8720
	v_add_f32_dpp v198, v198, v198 row_half_mirror row_mask:0xf bank_mask:0xf bound_ctrl:1
	v_add_f32_dpp v163, v207, v207 row_half_mirror row_mask:0xf bank_mask:0xf bound_ctrl:1
	ds_read2st64_b32 v[158:159], v161 offset0:2 offset1:3
	ds_write_b32 v162, v163 offset:0
	s_waitcnt lgkmcnt(5)
	v_pk_fma_f32 v[58:59], v[198:199], v[50:51], v[58:59] op_sel_hi:[0,1,1]
	v_pk_fma_f32 v[72:73], v[198:199], v[52:53], v[72:73] op_sel_hi:[0,1,1]
	v_pk_fma_f32 v[66:67], v[66:67], v[42:43], v[58:59]
	v_pk_fma_f32 v[64:65], v[64:65], v[44:45], v[72:73]
	v_pk_fma_f32 v[212:213], v[198:199], v[54:55], v[212:213] op_sel_hi:[0,1,1]
	v_pk_fma_f32 v[250:251], v[198:199], v[56:57], v[250:251] op_sel_hi:[0,1,1]
	v_pk_fma_f32 v[62:63], v[62:63], v[46:47], v[212:213]
	v_pk_fma_f32 v[60:61], v[60:61], v[48:49], v[250:251]
	ds_read_b128 v[50:53], v0 offset:20992
	ds_read_b128 v[54:57], v0 offset:21008
	ds_read_b128 v[42:45], v0 offset:4608
	ds_read_b128 v[46:49], v0 offset:4624
	v_pk_fma_f32 v[58:59], v[66:67], v[154:155], 0 op_sel_hi:[1,1,0]
	v_pk_fma_f32 v[72:73], v[64:65], v[156:157], 0 op_sel_hi:[1,1,0]
	v_pk_fma_f32 v[58:59], v[62:63], v[246:247], v[58:59]
	v_pk_fma_f32 v[72:73], v[60:61], v[248:249], v[72:73]
	ds_read_b128 v[154:157], v0 offset:512
	ds_read_b128 v[246:249], v0 offset:528
	v_pk_add_f32 v[58:59], v[58:59], v[72:73]
	ds_read_b128 v[200:203], v0 offset:17152
	ds_read_b128 v[230:233], v0 offset:17168
	s_waitcnt lgkmcnt(8)
; DI float oct_sum(float v) { v += dpp_f<0xB1>(v); v += dpp_f<0x4E>(v); v += dpp_f<0x141>(v); return v; }
; DI void scan_item(const Params& p, int b, int h, int half, char* smem, unsigned* pgen, unsigned kp) {
;     ...
;       for (int s4 = 0; s4 < 4; ++s4) {
;         const int s = sg + s4;
;         const f32x2* a2 = (const f32x2*)(Al + s * 64 + cg * 8);
;         const f32x2* w2 = (const f32x2*)(Wl + s * 64 + cg * 8);
;         const f32x2* b2 = (const f32x2*)(Bl + s * 64 + cg * 8);
;         const f32x2* k2 = (const f32x2*)(Kl + s * 64 + cg * 8);
;         const f32x2* r2 = (const f32x2*)(Rl + s * 64 + cg * 8);
;         f32x2 o[20];
; #pragma unroll
;         for (int i = 0; i < 4; ++i) { o[i] = a2[i]; o[4 + i] = w2[i]; o[8 + i] = b2[i]; o[12 + i] = k2[i]; o[16 + i] = r2[i]; }
;         const float vr = Vl[s * 64 + 32 * half + rp];
;         f32x2 p0 = St[0] * o[0], p1 = St[1] * o[1];
;         p0 = __builtin_elementwise_fma(St[2], o[2], p0); p1 = __builtin_elementwise_fma(St[3], o[3], p1);
;         const float sa = oct_sum((p0.x + p0.y) + (p1.x + p1.y));
;         const f32x2 sv = {sa, sa}, vv = {vr, vr};
;         f32x2 y0 = {0.f, 0.f}, y1 = {0.f, 0.f};
; #pragma unroll
;         for (int i = 0; i < 4; i += 2) {
;           St[i] = __builtin_elementwise_fma(St[i], o[4 + i], __builtin_elementwise_fma(sv, o[8 + i], vv * o[12 + i]));
;           St[i + 1] = __builtin_elementwise_fma(St[i + 1], o[5 + i], __builtin_elementwise_fma(sv, o[9 + i], vv * o[13 + i]));
;           y0 = __builtin_elementwise_fma(St[i], o[16 + i], y0);
;           y1 = __builtin_elementwise_fma(St[i + 1], o[17 + i], y1);
;         }
;         yy[s4] = oct_sum((y0.x + y0.y) + (y1.x + y1.y));
;       }
;       if (cg == 0) {
; #pragma unroll
;         for (int s4 = 0; s4 < 4; ++s4) Yl[(sg + s4) * 32 + rp] = yy[s4];
	v_pk_mul_f32 v[34:35], v[66:67], v[34:35]
	v_pk_mul_f32 v[36:37], v[64:65], v[36:37]
	v_pk_fma_f32 v[34:35], v[62:63], v[38:39], v[34:35]
	v_pk_fma_f32 v[36:37], v[60:61], v[40:41], v[36:37]
	v_pk_add_f32 v[34:35], v[34:35], v[36:37]
	v_add_f32_e32 v207, v58, v59
	v_add_f32_e32 v198, v34, v35
	v_pk_mul_f32 v[58:59], v[68:69], v[158:159] op_sel_hi:[1,0]
	v_pk_mul_f32 v[72:73], v[70:71], v[158:159] op_sel_hi:[1,0]
	ds_read_b128 v[68:71], v0 offset:8960
	v_add_f32_dpp v198, v198, v198 quad_perm:[1,0,3,2] row_mask:0xf bank_mask:0xf bound_ctrl:1
	v_add_f32_dpp v207, v207, v207 quad_perm:[1,0,3,2] row_mask:0xf bank_mask:0xf bound_ctrl:1
	v_pk_mul_f32 v[212:213], v[150:151], v[158:159] op_sel_hi:[1,0]
	v_add_f32_dpp v198, v198, v198 quad_perm:[2,3,0,1] row_mask:0xf bank_mask:0xf bound_ctrl:1
	v_add_f32_dpp v207, v207, v207 quad_perm:[2,3,0,1] row_mask:0xf bank_mask:0xf bound_ctrl:1
	v_pk_mul_f32 v[250:251], v[152:153], v[158:159] op_sel_hi:[1,0]
	ds_read_b128 v[150:153], v0 offset:8976
	v_add_f32_dpp v198, v198, v198 row_half_mirror row_mask:0xf bank_mask:0xf bound_ctrl:1
	v_add_f32_dpp v205, v207, v207 row_half_mirror row_mask:0xf bank_mask:0xf bound_ctrl:1
	ds_write_b32 v162, v205 offset:128
	s_waitcnt lgkmcnt(4)
	v_pk_fma_f32 v[58:59], v[198:199], v[50:51], v[58:59] op_sel_hi:[0,1,1]
	v_pk_fma_f32 v[72:73], v[198:199], v[52:53], v[72:73] op_sel_hi:[0,1,1]
	v_pk_fma_f32 v[66:67], v[66:67], v[42:43], v[58:59]
	v_pk_fma_f32 v[64:65], v[64:65], v[44:45], v[72:73]
	v_pk_fma_f32 v[212:213], v[198:199], v[54:55], v[212:213] op_sel_hi:[0,1,1]
	v_pk_fma_f32 v[250:251], v[198:199], v[56:57], v[250:251] op_sel_hi:[0,1,1]
	v_pk_fma_f32 v[62:63], v[62:63], v[46:47], v[212:213]
	v_pk_fma_f32 v[60:61], v[60:61], v[48:49], v[250:251]
	ds_read_b128 v[50:53], v0 offset:21248
	ds_read_b128 v[54:57], v0 offset:21264
	ds_read_b128 v[42:45], v0 offset:4864
	ds_read_b128 v[46:49], v0 offset:4880
	v_pk_fma_f32 v[58:59], v[66:67], v[154:155], 0 op_sel_hi:[1,1,0]
	v_pk_fma_f32 v[72:73], v[64:65], v[156:157], 0 op_sel_hi:[1,1,0]
	v_pk_fma_f32 v[58:59], v[62:63], v[246:247], v[58:59]
	v_pk_fma_f32 v[72:73], v[60:61], v[248:249], v[72:73]
	ds_read_b128 v[154:157], v0 offset:768
	ds_read_b128 v[246:249], v0 offset:784
	v_pk_add_f32 v[58:59], v[58:59], v[72:73]
	ds_read_b128 v[34:37], v0 offset:17408
	ds_read_b128 v[38:41], v0 offset:17424
	s_waitcnt lgkmcnt(8)
	v_pk_mul_f32 v[200:201], v[66:67], v[200:201]
	v_pk_mul_f32 v[202:203], v[64:65], v[202:203]
	v_pk_fma_f32 v[200:201], v[62:63], v[230:231], v[200:201]
	v_pk_fma_f32 v[202:203], v[60:61], v[232:233], v[202:203]
	v_pk_add_f32 v[200:201], v[200:201], v[202:203]
	v_add_f32_e32 v207, v58, v59
	v_add_f32_e32 v198, v200, v201
	v_mov_b32_e32 v232, v159
	v_pk_mul_f32 v[58:59], v[68:69], v[232:233] op_sel_hi:[1,0]
	v_pk_mul_f32 v[72:73], v[70:71], v[232:233] op_sel_hi:[1,0]
	ds_read_b128 v[68:71], v0 offset:9216
	v_add_f32_dpp v198, v198, v198 quad_perm:[1,0,3,2] row_mask:0xf bank_mask:0xf bound_ctrl:1
	v_add_f32_dpp v207, v207, v207 quad_perm:[1,0,3,2] row_mask:0xf bank_mask:0xf bound_ctrl:1
	v_pk_mul_f32 v[212:213], v[150:151], v[232:233] op_sel_hi:[1,0]
	v_add_f32_dpp v198, v198, v198 quad_perm:[2,3,0,1] row_mask:0xf bank_mask:0xf bound_ctrl:1
	v_add_f32_dpp v207, v207, v207 quad_perm:[2,3,0,1] row_mask:0xf bank_mask:0xf bound_ctrl:1
	v_pk_mul_f32 v[250:251], v[152:153], v[232:233] op_sel_hi:[1,0]
	ds_read_b128 v[150:153], v0 offset:9232
	v_add_f32_dpp v198, v198, v198 row_half_mirror row_mask:0xf bank_mask:0xf bound_ctrl:1
	v_add_f32_dpp v163, v207, v207 row_half_mirror row_mask:0xf bank_mask:0xf bound_ctrl:1
	ds_read2st64_b32 v[158:159], v161 offset0:4 offset1:5
	ds_write_b32 v162, v163 offset:256
	s_waitcnt lgkmcnt(5)
	v_pk_fma_f32 v[58:59], v[198:199], v[50:51], v[58:59] op_sel_hi:[0,1,1]
	v_pk_fma_f32 v[72:73], v[198:199], v[52:53], v[72:73] op_sel_hi:[0,1,1]
	v_pk_fma_f32 v[66:67], v[66:67], v[42:43], v[58:59]
	v_pk_fma_f32 v[64:65], v[64:65], v[44:45], v[72:73]
	v_pk_fma_f32 v[212:213], v[198:199], v[54:55], v[212:213] op_sel_hi:[0,1,1]
	v_pk_fma_f32 v[250:251], v[198:199], v[56:57], v[250:251] op_sel_hi:[0,1,1]
	v_pk_fma_f32 v[62:63], v[62:63], v[46:47], v[212:213]
	v_pk_fma_f32 v[60:61], v[60:61], v[48:49], v[250:251]
	ds_read_b128 v[50:53], v0 offset:21504
	ds_read_b128 v[54:57], v0 offset:21520
	ds_read_b128 v[42:45], v0 offset:5120
	ds_read_b128 v[46:49], v0 offset:5136
	v_pk_fma_f32 v[58:59], v[66:67], v[154:155], 0 op_sel_hi:[1,1,0]
	v_pk_fma_f32 v[72:73], v[64:65], v[156:157], 0 op_sel_hi:[1,1,0]
	v_pk_fma_f32 v[58:59], v[62:63], v[246:247], v[58:59]
	v_pk_fma_f32 v[72:73], v[60:61], v[248:249], v[72:73]
	ds_read_b128 v[154:157], v0 offset:1024
	ds_read_b128 v[246:249], v0 offset:1040
	v_pk_add_f32 v[58:59], v[58:59], v[72:73]
	ds_read_b128 v[200:203], v0 offset:17664
	ds_read_b128 v[230:233], v0 offset:17680
	s_waitcnt lgkmcnt(8)
	v_pk_mul_f32 v[34:35], v[66:67], v[34:35]
	v_pk_mul_f32 v[36:37], v[64:65], v[36:37]
	v_pk_fma_f32 v[34:35], v[62:63], v[38:39], v[34:35]
	v_pk_fma_f32 v[36:37], v[60:61], v[40:41], v[36:37]
	v_pk_add_f32 v[34:35], v[34:35], v[36:37]
	v_add_f32_e32 v207, v58, v59
	v_add_f32_e32 v198, v34, v35
	v_pk_mul_f32 v[58:59], v[68:69], v[158:159] op_sel_hi:[1,0]
	v_pk_mul_f32 v[72:73], v[70:71], v[158:159] op_sel_hi:[1,0]
	ds_read_b128 v[68:71], v0 offset:9472
	v_add_f32_dpp v198, v198, v198 quad_perm:[1,0,3,2] row_mask:0xf bank_mask:0xf bound_ctrl:1
	v_add_f32_dpp v207, v207, v207 quad_perm:[1,0,3,2] row_mask:0xf bank_mask:0xf bound_ctrl:1
	v_pk_mul_f32 v[212:213], v[150:151], v[158:159] op_sel_hi:[1,0]
	v_add_f32_dpp v198, v198, v198 quad_perm:[2,3,0,1] row_mask:0xf bank_mask:0xf bound_ctrl:1
	v_add_f32_dpp v207, v207, v207 quad_perm:[2,3,0,1] row_mask:0xf bank_mask:0xf bound_ctrl:1
	v_pk_mul_f32 v[250:251], v[152:153], v[158:159] op_sel_hi:[1,0]
	ds_read_b128 v[150:153], v0 offset:9488
	v_add_f32_dpp v198, v198, v198 row_half_mirror row_mask:0xf bank_mask:0xf bound_ctrl:1
	v_add_f32_dpp v205, v207, v207 row_half_mirror row_mask:0xf bank_mask:0xf bound_ctrl:1
	ds_write_b32 v162, v205 offset:384
	s_waitcnt lgkmcnt(4)
; DI float oct_sum(float v) { v += dpp_f<0xB1>(v); v += dpp_f<0x4E>(v); v += dpp_f<0x141>(v); return v; }
; DI void scan_item(const Params& p, int b, int h, int half, char* smem, unsigned* pgen, unsigned kp) {
;     ...
;       for (int s4 = 0; s4 < 4; ++s4) {
;         const int s = sg + s4;
;         const f32x2* a2 = (const f32x2*)(Al + s * 64 + cg * 8);
;         const f32x2* w2 = (const f32x2*)(Wl + s * 64 + cg * 8);
;         const f32x2* b2 = (const f32x2*)(Bl + s * 64 + cg * 8);
;         const f32x2* k2 = (const f32x2*)(Kl + s * 64 + cg * 8);
;         const f32x2* r2 = (const f32x2*)(Rl + s * 64 + cg * 8);
;         f32x2 o[20];
; #pragma unroll
;         for (int i = 0; i < 4; ++i) { o[i] = a2[i]; o[4 + i] = w2[i]; o[8 + i] = b2[i]; o[12 + i] = k2[i]; o[16 + i] = r2[i]; }
;         const float vr = Vl[s * 64 + 32 * half + rp];
;         f32x2 p0 = St[0] * o[0], p1 = St[1] * o[1];
;         p0 = __builtin_elementwise_fma(St[2], o[2], p0); p1 = __builtin_elementwise_fma(St[3], o[3], p1);
;         const float sa = oct_sum((p0.x + p0.y) + (p1.x + p1.y));
;         const f32x2 sv = {sa, sa}, vv = {vr, vr};
;         f32x2 y0 = {0.f, 0.f}, y1 = {0.f, 0.f};
; #pragma unroll
;         for (int i = 0; i < 4; i += 2) {
;           St[i] = __builtin_elementwise_fma(St[i], o[4 + i], __builtin_elementwise_fma(sv, o[8 + i], vv * o[12 + i]));
;           St[i + 1] = __builtin_elementwise_fma(St[i + 1], o[5 + i], __builtin_elementwise_fma(sv, o[9 + i], vv * o[13 + i]));
;           y0 = __builtin_elementwise_fma(St[i], o[16 + i], y0);
;           y1 = __builtin_elementwise_fma(St[i + 1], o[17 + i], y1);
;         }
;         yy[s4] = oct_sum((y0.x + y0.y) + (y1.x + y1.y));
;       }
;       if (cg == 0) {
; #pragma unroll
;         for (int s4 = 0; s4 < 4; ++s4) Yl[(sg + s4) * 32 + rp] = yy[s4];
	v_pk_fma_f32 v[58:59], v[198:199], v[50:51], v[58:59] op_sel_hi:[0,1,1]
	v_pk_fma_f32 v[72:73], v[198:199], v[52:53], v[72:73] op_sel_hi:[0,1,1]
	v_pk_fma_f32 v[66:67], v[66:67], v[42:43], v[58:59]
	v_pk_fma_f32 v[64:65], v[64:65], v[44:45], v[72:73]
	v_pk_fma_f32 v[212:213], v[198:199], v[54:55], v[212:213] op_sel_hi:[0,1,1]
	v_pk_fma_f32 v[250:251], v[198:199], v[56:57], v[250:251] op_sel_hi:[0,1,1]
	v_pk_fma_f32 v[62:63], v[62:63], v[46:47], v[212:213]
	v_pk_fma_f32 v[60:61], v[60:61], v[48:49], v[250:251]
	ds_read_b128 v[50:53], v0 offset:21760
	ds_read_b128 v[54:57], v0 offset:21776
	ds_read_b128 v[42:45], v0 offset:5376
	ds_read_b128 v[46:49], v0 offset:5392
	v_pk_fma_f32 v[58:59], v[66:67], v[154:155], 0 op_sel_hi:[1,1,0]
	v_pk_fma_f32 v[72:73], v[64:65], v[156:157], 0 op_sel_hi:[1,1,0]
	v_pk_fma_f32 v[58:59], v[62:63], v[246:247], v[58:59]
	v_pk_fma_f32 v[72:73], v[60:61], v[248:249], v[72:73]
	ds_read_b128 v[154:157], v0 offset:1280
	ds_read_b128 v[246:249], v0 offset:1296
	v_pk_add_f32 v[58:59], v[58:59], v[72:73]
	ds_read_b128 v[34:37], v0 offset:17920
	ds_read_b128 v[38:41], v0 offset:17936
	s_waitcnt lgkmcnt(8)
	v_pk_mul_f32 v[200:201], v[66:67], v[200:201]
	v_pk_mul_f32 v[202:203], v[64:65], v[202:203]
	v_pk_fma_f32 v[200:201], v[62:63], v[230:231], v[200:201]
	v_pk_fma_f32 v[202:203], v[60:61], v[232:233], v[202:203]
	v_pk_add_f32 v[200:201], v[200:201], v[202:203]
	v_add_f32_e32 v207, v58, v59
	v_add_f32_e32 v198, v200, v201
	v_mov_b32_e32 v232, v159
	v_pk_mul_f32 v[58:59], v[68:69], v[232:233] op_sel_hi:[1,0]
	v_pk_mul_f32 v[72:73], v[70:71], v[232:233] op_sel_hi:[1,0]
	ds_read_b128 v[68:71], v0 offset:9728
	v_add_f32_dpp v198, v198, v198 quad_perm:[1,0,3,2] row_mask:0xf bank_mask:0xf bound_ctrl:1
	v_add_f32_dpp v207, v207, v207 quad_perm:[1,0,3,2] row_mask:0xf bank_mask:0xf bound_ctrl:1
	v_pk_mul_f32 v[212:213], v[150:151], v[232:233] op_sel_hi:[1,0]
	v_add_f32_dpp v198, v198, v198 quad_perm:[2,3,0,1] row_mask:0xf bank_mask:0xf bound_ctrl:1
	v_add_f32_dpp v207, v207, v207 quad_perm:[2,3,0,1] row_mask:0xf bank_mask:0xf bound_ctrl:1
	v_pk_mul_f32 v[250:251], v[152:153], v[232:233] op_sel_hi:[1,0]
	ds_read_b128 v[150:153], v0 offset:9744
	v_add_f32_dpp v198, v198, v198 row_half_mirror row_mask:0xf bank_mask:0xf bound_ctrl:1
	v_add_f32_dpp v163, v207, v207 row_half_mirror row_mask:0xf bank_mask:0xf bound_ctrl:1
	ds_read2st64_b32 v[158:159], v161 offset0:6 offset1:7
	ds_write_b32 v162, v163 offset:512
	s_waitcnt lgkmcnt(5)
	v_pk_fma_f32 v[58:59], v[198:199], v[50:51], v[58:59] op_sel_hi:[0,1,1]
	v_pk_fma_f32 v[72:73], v[198:199], v[52:53], v[72:73] op_sel_hi:[0,1,1]
	v_pk_fma_f32 v[66:67], v[66:67], v[42:43], v[58:59]
	v_pk_fma_f32 v[64:65], v[64:65], v[44:45], v[72:73]
	v_pk_fma_f32 v[212:213], v[198:199], v[54:55], v[212:213] op_sel_hi:[0,1,1]
	v_pk_fma_f32 v[250:251], v[198:199], v[56:57], v[250:251] op_sel_hi:[0,1,1]
	v_pk_fma_f32 v[62:63], v[62:63], v[46:47], v[212:213]
	v_pk_fma_f32 v[60:61], v[60:61], v[48:49], v[250:251]
	ds_read_b128 v[50:53], v0 offset:22016
	ds_read_b128 v[54:57], v0 offset:22032
	ds_read_b128 v[42:45], v0 offset:5632
	ds_read_b128 v[46:49], v0 offset:5648
	v_pk_fma_f32 v[58:59], v[66:67], v[154:155], 0 op_sel_hi:[1,1,0]
	v_pk_fma_f32 v[72:73], v[64:65], v[156:157], 0 op_sel_hi:[1,1,0]
	v_pk_fma_f32 v[58:59], v[62:63], v[246:247], v[58:59]
	v_pk_fma_f32 v[72:73], v[60:61], v[248:249], v[72:73]
	ds_read_b128 v[154:157], v0 offset:1536
	ds_read_b128 v[246:249], v0 offset:1552
	v_pk_add_f32 v[58:59], v[58:59], v[72:73]
	ds_read_b128 v[200:203], v0 offset:18176
	ds_read_b128 v[230:233], v0 offset:18192
	s_waitcnt lgkmcnt(8)
	v_pk_mul_f32 v[34:35], v[66:67], v[34:35]
	v_pk_mul_f32 v[36:37], v[64:65], v[36:37]
	v_pk_fma_f32 v[34:35], v[62:63], v[38:39], v[34:35]
	v_pk_fma_f32 v[36:37], v[60:61], v[40:41], v[36:37]
	v_pk_add_f32 v[34:35], v[34:35], v[36:37]
	v_add_f32_e32 v207, v58, v59
	v_add_f32_e32 v198, v34, v35
	v_pk_mul_f32 v[58:59], v[68:69], v[158:159] op_sel_hi:[1,0]
	v_pk_mul_f32 v[72:73], v[70:71], v[158:159] op_sel_hi:[1,0]
	ds_read_b128 v[68:71], v0 offset:9984
	v_add_f32_dpp v198, v198, v198 quad_perm:[1,0,3,2] row_mask:0xf bank_mask:0xf bound_ctrl:1
	v_add_f32_dpp v207, v207, v207 quad_perm:[1,0,3,2] row_mask:0xf bank_mask:0xf bound_ctrl:1
	v_pk_mul_f32 v[212:213], v[150:151], v[158:159] op_sel_hi:[1,0]
	v_add_f32_dpp v198, v198, v198 quad_perm:[2,3,0,1] row_mask:0xf bank_mask:0xf bound_ctrl:1
	v_add_f32_dpp v207, v207, v207 quad_perm:[2,3,0,1] row_mask:0xf bank_mask:0xf bound_ctrl:1
	v_pk_mul_f32 v[250:251], v[152:153], v[158:159] op_sel_hi:[1,0]
	ds_read_b128 v[150:153], v0 offset:10000
	v_add_f32_dpp v198, v198, v198 row_half_mirror row_mask:0xf bank_mask:0xf bound_ctrl:1
	v_add_f32_dpp v205, v207, v207 row_half_mirror row_mask:0xf bank_mask:0xf bound_ctrl:1
	ds_write_b32 v162, v205 offset:640
	s_waitcnt lgkmcnt(4)
	v_pk_fma_f32 v[58:59], v[198:199], v[50:51], v[58:59] op_sel_hi:[0,1,1]
	v_pk_fma_f32 v[72:73], v[198:199], v[52:53], v[72:73] op_sel_hi:[0,1,1]
	v_pk_fma_f32 v[66:67], v[66:67], v[42:43], v[58:59]
	v_pk_fma_f32 v[64:65], v[64:65], v[44:45], v[72:73]
	v_pk_fma_f32 v[212:213], v[198:199], v[54:55], v[212:213] op_sel_hi:[0,1,1]
	v_pk_fma_f32 v[250:251], v[198:199], v[56:57], v[250:251] op_sel_hi:[0,1,1]
	v_pk_fma_f32 v[62:63], v[62:63], v[46:47], v[212:213]
	v_pk_fma_f32 v[60:61], v[60:61], v[48:49], v[250:251]
	ds_read_b128 v[50:53], v0 offset:22272
	ds_read_b128 v[54:57], v0 offset:22288
	ds_read_b128 v[42:45], v0 offset:5888
	ds_read_b128 v[46:49], v0 offset:5904
	v_pk_fma_f32 v[58:59], v[66:67], v[154:155], 0 op_sel_hi:[1,1,0]
	v_pk_fma_f32 v[72:73], v[64:65], v[156:157], 0 op_sel_hi:[1,1,0]
	v_pk_fma_f32 v[58:59], v[62:63], v[246:247], v[58:59]
	v_pk_fma_f32 v[72:73], v[60:61], v[248:249], v[72:73]
	ds_read_b128 v[154:157], v0 offset:1792
	ds_read_b128 v[246:249], v0 offset:1808
	v_pk_add_f32 v[58:59], v[58:59], v[72:73]
	ds_read_b128 v[34:37], v0 offset:18432
	ds_read_b128 v[38:41], v0 offset:18448
	s_waitcnt lgkmcnt(8)
; DI float oct_sum(float v) { v += dpp_f<0xB1>(v); v += dpp_f<0x4E>(v); v += dpp_f<0x141>(v); return v; }
; DI void scan_item(const Params& p, int b, int h, int half, char* smem, unsigned* pgen, unsigned kp) {
;     ...
;       for (int s4 = 0; s4 < 4; ++s4) {
;         const int s = sg + s4;
;         const f32x2* a2 = (const f32x2*)(Al + s * 64 + cg * 8);
;         const f32x2* w2 = (const f32x2*)(Wl + s * 64 + cg * 8);
;         const f32x2* b2 = (const f32x2*)(Bl + s * 64 + cg * 8);
;         const f32x2* k2 = (const f32x2*)(Kl + s * 64 + cg * 8);
;         const f32x2* r2 = (const f32x2*)(Rl + s * 64 + cg * 8);
;         f32x2 o[20];
; #pragma unroll
;         for (int i = 0; i < 4; ++i) { o[i] = a2[i]; o[4 + i] = w2[i]; o[8 + i] = b2[i]; o[12 + i] = k2[i]; o[16 + i] = r2[i]; }
;         const float vr = Vl[s * 64 + 32 * half + rp];
;         f32x2 p0 = St[0] * o[0], p1 = St[1] * o[1];
;         p0 = __builtin_elementwise_fma(St[2], o[2], p0); p1 = __builtin_elementwise_fma(St[3], o[3], p1);
;         const float sa = oct_sum((p0.x + p0.y) + (p1.x + p1.y));
;         const f32x2 sv = {sa, sa}, vv = {vr, vr};
;         f32x2 y0 = {0.f, 0.f}, y1 = {0.f, 0.f};
; #pragma unroll
;         for (int i = 0; i < 4; i += 2) {
;           St[i] = __builtin_elementwise_fma(St[i], o[4 + i], __builtin_elementwise_fma(sv, o[8 + i], vv * o[12 + i]));
;           St[i + 1] = __builtin_elementwise_fma(St[i + 1], o[5 + i], __builtin_elementwise_fma(sv, o[9 + i], vv * o[13 + i]));
;           y0 = __builtin_elementwise_fma(St[i], o[16 + i], y0);
;           y1 = __builtin_elementwise_fma(St[i + 1], o[17 + i], y1);
;         }
;         yy[s4] = oct_sum((y0.x + y0.y) + (y1.x + y1.y));
;       }
	v_pk_mul_f32 v[200:201], v[66:67], v[200:201]
	v_pk_mul_f32 v[202:203], v[64:65], v[202:203]
	v_pk_fma_f32 v[200:201], v[62:63], v[230:231], v[200:201]
	v_pk_fma_f32 v[202:203], v[60:61], v[232:233], v[202:203]
	v_pk_add_f32 v[200:201], v[200:201], v[202:203]
	v_add_f32_e32 v207, v58, v59
	v_add_f32_e32 v198, v200, v201
	v_mov_b32_e32 v232, v159
	v_pk_mul_f32 v[58:59], v[68:69], v[232:233] op_sel_hi:[1,0]
	v_pk_mul_f32 v[72:73], v[70:71], v[232:233] op_sel_hi:[1,0]
	ds_read_b128 v[68:71], v0 offset:10240
	v_add_f32_dpp v198, v198, v198 quad_perm:[1,0,3,2] row_mask:0xf bank_mask:0xf bound_ctrl:1
	v_add_f32_dpp v207, v207, v207 quad_perm:[1,0,3,2] row_mask:0xf bank_mask:0xf bound_ctrl:1
	v_pk_mul_f32 v[212:213], v[150:151], v[232:233] op_sel_hi:[1,0]
	v_add_f32_dpp v198, v198, v198 quad_perm:[2,3,0,1] row_mask:0xf bank_mask:0xf bound_ctrl:1
	v_add_f32_dpp v207, v207, v207 quad_perm:[2,3,0,1] row_mask:0xf bank_mask:0xf bound_ctrl:1
	v_pk_mul_f32 v[250:251], v[152:153], v[232:233] op_sel_hi:[1,0]
	ds_read_b128 v[150:153], v0 offset:10256
	v_add_f32_dpp v198, v198, v198 row_half_mirror row_mask:0xf bank_mask:0xf bound_ctrl:1
	v_add_f32_dpp v163, v207, v207 row_half_mirror row_mask:0xf bank_mask:0xf bound_ctrl:1
	ds_read2st64_b32 v[158:159], v161 offset0:8 offset1:9
	ds_write_b32 v162, v163 offset:768
	s_waitcnt lgkmcnt(5)
	v_pk_fma_f32 v[58:59], v[198:199], v[50:51], v[58:59] op_sel_hi:[0,1,1]
	v_pk_fma_f32 v[72:73], v[198:199], v[52:53], v[72:73] op_sel_hi:[0,1,1]
	v_pk_fma_f32 v[66:67], v[66:67], v[42:43], v[58:59]
	v_pk_fma_f32 v[64:65], v[64:65], v[44:45], v[72:73]
	v_pk_fma_f32 v[212:213], v[198:199], v[54:55], v[212:213] op_sel_hi:[0,1,1]
	v_pk_fma_f32 v[250:251], v[198:199], v[56:57], v[250:251] op_sel_hi:[0,1,1]
	v_pk_fma_f32 v[62:63], v[62:63], v[46:47], v[212:213]
	v_pk_fma_f32 v[60:61], v[60:61], v[48:49], v[250:251]
	ds_read_b128 v[50:53], v0 offset:22528
	ds_read_b128 v[54:57], v0 offset:22544
	ds_read_b128 v[42:45], v0 offset:6144
	ds_read_b128 v[46:49], v0 offset:6160
	v_pk_fma_f32 v[58:59], v[66:67], v[154:155], 0 op_sel_hi:[1,1,0]
	v_pk_fma_f32 v[72:73], v[64:65], v[156:157], 0 op_sel_hi:[1,1,0]
	v_pk_fma_f32 v[58:59], v[62:63], v[246:247], v[58:59]
	v_pk_fma_f32 v[72:73], v[60:61], v[248:249], v[72:73]
	ds_read_b128 v[154:157], v0 offset:2048
	ds_read_b128 v[246:249], v0 offset:2064
	v_pk_add_f32 v[58:59], v[58:59], v[72:73]
	ds_read_b128 v[200:203], v0 offset:18688
	ds_read_b128 v[230:233], v0 offset:18704
	s_waitcnt lgkmcnt(8)
	v_pk_mul_f32 v[34:35], v[66:67], v[34:35]
	v_pk_mul_f32 v[36:37], v[64:65], v[36:37]
	v_pk_fma_f32 v[34:35], v[62:63], v[38:39], v[34:35]
	v_pk_fma_f32 v[36:37], v[60:61], v[40:41], v[36:37]
	v_pk_add_f32 v[34:35], v[34:35], v[36:37]
	v_add_f32_e32 v207, v58, v59
	v_add_f32_e32 v198, v34, v35
	v_pk_mul_f32 v[58:59], v[68:69], v[158:159] op_sel_hi:[1,0]
	v_pk_mul_f32 v[72:73], v[70:71], v[158:159] op_sel_hi:[1,0]
	ds_read_b128 v[68:71], v0 offset:10496
	v_add_f32_dpp v198, v198, v198 quad_perm:[1,0,3,2] row_mask:0xf bank_mask:0xf bound_ctrl:1
	v_add_f32_dpp v207, v207, v207 quad_perm:[1,0,3,2] row_mask:0xf bank_mask:0xf bound_ctrl:1
	v_pk_mul_f32 v[212:213], v[150:151], v[158:159] op_sel_hi:[1,0]
	v_add_f32_dpp v198, v198, v198 quad_perm:[2,3,0,1] row_mask:0xf bank_mask:0xf bound_ctrl:1
	v_add_f32_dpp v207, v207, v207 quad_perm:[2,3,0,1] row_mask:0xf bank_mask:0xf bound_ctrl:1
	v_pk_mul_f32 v[250:251], v[152:153], v[158:159] op_sel_hi:[1,0]
	ds_read_b128 v[150:153], v0 offset:10512
	v_add_f32_dpp v198, v198, v198 row_half_mirror row_mask:0xf bank_mask:0xf bound_ctrl:1
	v_add_f32_dpp v205, v207, v207 row_half_mirror row_mask:0xf bank_mask:0xf bound_ctrl:1
	ds_write_b32 v162, v205 offset:896
	s_waitcnt lgkmcnt(4)
	v_pk_fma_f32 v[58:59], v[198:199], v[50:51], v[58:59] op_sel_hi:[0,1,1]
	v_pk_fma_f32 v[72:73], v[198:199], v[52:53], v[72:73] op_sel_hi:[0,1,1]
	v_pk_fma_f32 v[66:67], v[66:67], v[42:43], v[58:59]
	v_pk_fma_f32 v[64:65], v[64:65], v[44:45], v[72:73]
	v_pk_fma_f32 v[212:213], v[198:199], v[54:55], v[212:213] op_sel_hi:[0,1,1]
	v_pk_fma_f32 v[250:251], v[198:199], v[56:57], v[250:251] op_sel_hi:[0,1,1]
	v_pk_fma_f32 v[62:63], v[62:63], v[46:47], v[212:213]
	v_pk_fma_f32 v[60:61], v[60:61], v[48:49], v[250:251]
	ds_read_b128 v[50:53], v0 offset:22784
	ds_read_b128 v[54:57], v0 offset:22800
	ds_read_b128 v[42:45], v0 offset:6400
	ds_read_b128 v[46:49], v0 offset:6416
	v_pk_fma_f32 v[58:59], v[66:67], v[154:155], 0 op_sel_hi:[1,1,0]
	v_pk_fma_f32 v[72:73], v[64:65], v[156:157], 0 op_sel_hi:[1,1,0]
	v_pk_fma_f32 v[58:59], v[62:63], v[246:247], v[58:59]
	v_pk_fma_f32 v[72:73], v[60:61], v[248:249], v[72:73]
	ds_read_b128 v[154:157], v0 offset:2304
	ds_read_b128 v[246:249], v0 offset:2320
	v_pk_add_f32 v[58:59], v[58:59], v[72:73]
	ds_read_b128 v[34:37], v0 offset:18944
	ds_read_b128 v[38:41], v0 offset:18960
	s_waitcnt lgkmcnt(8)
	v_pk_mul_f32 v[200:201], v[66:67], v[200:201]
	v_pk_mul_f32 v[202:203], v[64:65], v[202:203]
	v_pk_fma_f32 v[200:201], v[62:63], v[230:231], v[200:201]
	v_pk_fma_f32 v[202:203], v[60:61], v[232:233], v[202:203]
	v_pk_add_f32 v[200:201], v[200:201], v[202:203]
	v_add_f32_e32 v207, v58, v59
	v_add_f32_e32 v198, v200, v201
	v_mov_b32_e32 v232, v159
	v_pk_mul_f32 v[58:59], v[68:69], v[232:233] op_sel_hi:[1,0]
	v_pk_mul_f32 v[72:73], v[70:71], v[232:233] op_sel_hi:[1,0]
	ds_read_b128 v[68:71], v0 offset:10752
	v_add_f32_dpp v198, v198, v198 quad_perm:[1,0,3,2] row_mask:0xf bank_mask:0xf bound_ctrl:1
	v_add_f32_dpp v207, v207, v207 quad_perm:[1,0,3,2] row_mask:0xf bank_mask:0xf bound_ctrl:1
	v_pk_mul_f32 v[212:213], v[150:151], v[232:233] op_sel_hi:[1,0]
	v_add_f32_dpp v198, v198, v198 quad_perm:[2,3,0,1] row_mask:0xf bank_mask:0xf bound_ctrl:1
	v_add_f32_dpp v207, v207, v207 quad_perm:[2,3,0,1] row_mask:0xf bank_mask:0xf bound_ctrl:1
	v_pk_mul_f32 v[250:251], v[152:153], v[232:233] op_sel_hi:[1,0]
	ds_read_b128 v[150:153], v0 offset:10768
	v_add_f32_dpp v198, v198, v198 row_half_mirror row_mask:0xf bank_mask:0xf bound_ctrl:1
	v_add_f32_dpp v163, v207, v207 row_half_mirror row_mask:0xf bank_mask:0xf bound_ctrl:1
	ds_read2st64_b32 v[158:159], v161 offset0:10 offset1:11
	ds_write_b32 v162, v163 offset:1024
	s_waitcnt lgkmcnt(5)
; DI float oct_sum(float v) { v += dpp_f<0xB1>(v); v += dpp_f<0x4E>(v); v += dpp_f<0x141>(v); return v; }
; DI void scan_item(const Params& p, int b, int h, int half, char* smem, unsigned* pgen, unsigned kp) {
;     ...
;       for (int s4 = 0; s4 < 4; ++s4) {
;         const int s = sg + s4;
;         const f32x2* a2 = (const f32x2*)(Al + s * 64 + cg * 8);
;         const f32x2* w2 = (const f32x2*)(Wl + s * 64 + cg * 8);
;         const f32x2* b2 = (const f32x2*)(Bl + s * 64 + cg * 8);
;         const f32x2* k2 = (const f32x2*)(Kl + s * 64 + cg * 8);
;         const f32x2* r2 = (const f32x2*)(Rl + s * 64 + cg * 8);
;         f32x2 o[20];
; #pragma unroll
;         for (int i = 0; i < 4; ++i) { o[i] = a2[i]; o[4 + i] = w2[i]; o[8 + i] = b2[i]; o[12 + i] = k2[i]; o[16 + i] = r2[i]; }
;         const float vr = Vl[s * 64 + 32 * half + rp];
;         f32x2 p0 = St[0] * o[0], p1 = St[1] * o[1];
;         p0 = __builtin_elementwise_fma(St[2], o[2], p0); p1 = __builtin_elementwise_fma(St[3], o[3], p1);
;         const float sa = oct_sum((p0.x + p0.y) + (p1.x + p1.y));
;         const f32x2 sv = {sa, sa}, vv = {vr, vr};
;         f32x2 y0 = {0.f, 0.f}, y1 = {0.f, 0.f};
; #pragma unroll
;         for (int i = 0; i < 4; i += 2) {
;           St[i] = __builtin_elementwise_fma(St[i], o[4 + i], __builtin_elementwise_fma(sv, o[8 + i], vv * o[12 + i]));
;           St[i + 1] = __builtin_elementwise_fma(St[i + 1], o[5 + i], __builtin_elementwise_fma(sv, o[9 + i], vv * o[13 + i]));
;           y0 = __builtin_elementwise_fma(St[i], o[16 + i], y0);
;           y1 = __builtin_elementwise_fma(St[i + 1], o[17 + i], y1);
;         }
;         yy[s4] = oct_sum((y0.x + y0.y) + (y1.x + y1.y));
;       }
	v_pk_fma_f32 v[58:59], v[198:199], v[50:51], v[58:59] op_sel_hi:[0,1,1]
	v_pk_fma_f32 v[72:73], v[198:199], v[52:53], v[72:73] op_sel_hi:[0,1,1]
	v_pk_fma_f32 v[66:67], v[66:67], v[42:43], v[58:59]
	v_pk_fma_f32 v[64:65], v[64:65], v[44:45], v[72:73]
	v_pk_fma_f32 v[212:213], v[198:199], v[54:55], v[212:213] op_sel_hi:[0,1,1]
	v_pk_fma_f32 v[250:251], v[198:199], v[56:57], v[250:251] op_sel_hi:[0,1,1]
	v_pk_fma_f32 v[62:63], v[62:63], v[46:47], v[212:213]
	v_pk_fma_f32 v[60:61], v[60:61], v[48:49], v[250:251]
	ds_read_b128 v[50:53], v0 offset:23040
	ds_read_b128 v[54:57], v0 offset:23056
	ds_read_b128 v[42:45], v0 offset:6656
	ds_read_b128 v[46:49], v0 offset:6672
	v_pk_fma_f32 v[58:59], v[66:67], v[154:155], 0 op_sel_hi:[1,1,0]
	v_pk_fma_f32 v[72:73], v[64:65], v[156:157], 0 op_sel_hi:[1,1,0]
	v_pk_fma_f32 v[58:59], v[62:63], v[246:247], v[58:59]
	v_pk_fma_f32 v[72:73], v[60:61], v[248:249], v[72:73]
	ds_read_b128 v[154:157], v0 offset:2560
	ds_read_b128 v[246:249], v0 offset:2576
	v_pk_add_f32 v[58:59], v[58:59], v[72:73]
	ds_read_b128 v[200:203], v0 offset:19200
	ds_read_b128 v[230:233], v0 offset:19216
	s_waitcnt lgkmcnt(8)
	v_pk_mul_f32 v[34:35], v[66:67], v[34:35]
	v_pk_mul_f32 v[36:37], v[64:65], v[36:37]
	v_pk_fma_f32 v[34:35], v[62:63], v[38:39], v[34:35]
	v_pk_fma_f32 v[36:37], v[60:61], v[40:41], v[36:37]
	v_pk_add_f32 v[34:35], v[34:35], v[36:37]
	v_add_f32_e32 v207, v58, v59
	v_add_f32_e32 v198, v34, v35
	v_pk_mul_f32 v[58:59], v[68:69], v[158:159] op_sel_hi:[1,0]
	v_pk_mul_f32 v[72:73], v[70:71], v[158:159] op_sel_hi:[1,0]
	ds_read_b128 v[68:71], v0 offset:11008
	v_add_f32_dpp v198, v198, v198 quad_perm:[1,0,3,2] row_mask:0xf bank_mask:0xf bound_ctrl:1
	v_add_f32_dpp v207, v207, v207 quad_perm:[1,0,3,2] row_mask:0xf bank_mask:0xf bound_ctrl:1
	v_pk_mul_f32 v[212:213], v[150:151], v[158:159] op_sel_hi:[1,0]
	v_add_f32_dpp v198, v198, v198 quad_perm:[2,3,0,1] row_mask:0xf bank_mask:0xf bound_ctrl:1
	v_add_f32_dpp v207, v207, v207 quad_perm:[2,3,0,1] row_mask:0xf bank_mask:0xf bound_ctrl:1
	v_pk_mul_f32 v[250:251], v[152:153], v[158:159] op_sel_hi:[1,0]
	ds_read_b128 v[150:153], v0 offset:11024
	v_add_f32_dpp v198, v198, v198 row_half_mirror row_mask:0xf bank_mask:0xf bound_ctrl:1
	v_add_f32_dpp v205, v207, v207 row_half_mirror row_mask:0xf bank_mask:0xf bound_ctrl:1
	ds_write_b32 v162, v205 offset:1152
	s_waitcnt lgkmcnt(4)
	v_pk_fma_f32 v[58:59], v[198:199], v[50:51], v[58:59] op_sel_hi:[0,1,1]
	v_pk_fma_f32 v[72:73], v[198:199], v[52:53], v[72:73] op_sel_hi:[0,1,1]
	v_pk_fma_f32 v[66:67], v[66:67], v[42:43], v[58:59]
	v_pk_fma_f32 v[64:65], v[64:65], v[44:45], v[72:73]
	v_pk_fma_f32 v[212:213], v[198:199], v[54:55], v[212:213] op_sel_hi:[0,1,1]
	v_pk_fma_f32 v[250:251], v[198:199], v[56:57], v[250:251] op_sel_hi:[0,1,1]
	v_pk_fma_f32 v[62:63], v[62:63], v[46:47], v[212:213]
	v_pk_fma_f32 v[60:61], v[60:61], v[48:49], v[250:251]
	ds_read_b128 v[50:53], v0 offset:23296
	ds_read_b128 v[54:57], v0 offset:23312
	ds_read_b128 v[42:45], v0 offset:6912
	ds_read_b128 v[46:49], v0 offset:6928
	v_pk_fma_f32 v[58:59], v[66:67], v[154:155], 0 op_sel_hi:[1,1,0]
	v_pk_fma_f32 v[72:73], v[64:65], v[156:157], 0 op_sel_hi:[1,1,0]
	v_pk_fma_f32 v[58:59], v[62:63], v[246:247], v[58:59]
	v_pk_fma_f32 v[72:73], v[60:61], v[248:249], v[72:73]
	ds_read_b128 v[154:157], v0 offset:2816
	ds_read_b128 v[246:249], v0 offset:2832
	v_pk_add_f32 v[58:59], v[58:59], v[72:73]
	ds_read_b128 v[34:37], v0 offset:19456
	ds_read_b128 v[38:41], v0 offset:19472
	s_waitcnt lgkmcnt(8)
	v_pk_mul_f32 v[200:201], v[66:67], v[200:201]
	v_pk_mul_f32 v[202:203], v[64:65], v[202:203]
	v_pk_fma_f32 v[200:201], v[62:63], v[230:231], v[200:201]
	v_pk_fma_f32 v[202:203], v[60:61], v[232:233], v[202:203]
	v_pk_add_f32 v[200:201], v[200:201], v[202:203]
	v_add_f32_e32 v207, v58, v59
	v_add_f32_e32 v198, v200, v201
	v_mov_b32_e32 v232, v159
	v_pk_mul_f32 v[58:59], v[68:69], v[232:233] op_sel_hi:[1,0]
	v_pk_mul_f32 v[72:73], v[70:71], v[232:233] op_sel_hi:[1,0]
	ds_read_b128 v[68:71], v0 offset:11264
	v_add_f32_dpp v198, v198, v198 quad_perm:[1,0,3,2] row_mask:0xf bank_mask:0xf bound_ctrl:1
	v_add_f32_dpp v207, v207, v207 quad_perm:[1,0,3,2] row_mask:0xf bank_mask:0xf bound_ctrl:1
	v_pk_mul_f32 v[212:213], v[150:151], v[232:233] op_sel_hi:[1,0]
	v_add_f32_dpp v198, v198, v198 quad_perm:[2,3,0,1] row_mask:0xf bank_mask:0xf bound_ctrl:1
	v_add_f32_dpp v207, v207, v207 quad_perm:[2,3,0,1] row_mask:0xf bank_mask:0xf bound_ctrl:1
	v_pk_mul_f32 v[250:251], v[152:153], v[232:233] op_sel_hi:[1,0]
	ds_read_b128 v[150:153], v0 offset:11280
	v_add_f32_dpp v198, v198, v198 row_half_mirror row_mask:0xf bank_mask:0xf bound_ctrl:1
	v_add_f32_dpp v163, v207, v207 row_half_mirror row_mask:0xf bank_mask:0xf bound_ctrl:1
	ds_read2st64_b32 v[158:159], v161 offset0:12 offset1:13
	ds_write_b32 v162, v163 offset:1280
	s_waitcnt lgkmcnt(5)
	v_pk_fma_f32 v[58:59], v[198:199], v[50:51], v[58:59] op_sel_hi:[0,1,1]
	v_pk_fma_f32 v[72:73], v[198:199], v[52:53], v[72:73] op_sel_hi:[0,1,1]
	v_pk_fma_f32 v[66:67], v[66:67], v[42:43], v[58:59]
	v_pk_fma_f32 v[64:65], v[64:65], v[44:45], v[72:73]
	v_pk_fma_f32 v[212:213], v[198:199], v[54:55], v[212:213] op_sel_hi:[0,1,1]
	v_pk_fma_f32 v[250:251], v[198:199], v[56:57], v[250:251] op_sel_hi:[0,1,1]
	v_pk_fma_f32 v[62:63], v[62:63], v[46:47], v[212:213]
	v_pk_fma_f32 v[60:61], v[60:61], v[48:49], v[250:251]
	ds_read_b128 v[50:53], v0 offset:23552
	ds_read_b128 v[54:57], v0 offset:23568
	ds_read_b128 v[42:45], v0 offset:7168
	ds_read_b128 v[46:49], v0 offset:7184
	v_pk_fma_f32 v[58:59], v[66:67], v[154:155], 0 op_sel_hi:[1,1,0]
	v_pk_fma_f32 v[72:73], v[64:65], v[156:157], 0 op_sel_hi:[1,1,0]
	v_pk_fma_f32 v[58:59], v[62:63], v[246:247], v[58:59]
	v_pk_fma_f32 v[72:73], v[60:61], v[248:249], v[72:73]
	ds_read_b128 v[154:157], v0 offset:3072
	ds_read_b128 v[246:249], v0 offset:3088
	v_pk_add_f32 v[58:59], v[58:59], v[72:73]
	ds_read_b128 v[200:203], v0 offset:19712
	ds_read_b128 v[230:233], v0 offset:19728
	s_waitcnt lgkmcnt(8)
; DI float oct_sum(float v) { v += dpp_f<0xB1>(v); v += dpp_f<0x4E>(v); v += dpp_f<0x141>(v); return v; }
; DI void scan_item(const Params& p, int b, int h, int half, char* smem, unsigned* pgen, unsigned kp) {
;     ...
;       for (int s4 = 0; s4 < 4; ++s4) {
;         const int s = sg + s4;
;         const f32x2* a2 = (const f32x2*)(Al + s * 64 + cg * 8);
;         const f32x2* w2 = (const f32x2*)(Wl + s * 64 + cg * 8);
;         const f32x2* b2 = (const f32x2*)(Bl + s * 64 + cg * 8);
;         const f32x2* k2 = (const f32x2*)(Kl + s * 64 + cg * 8);
;         const f32x2* r2 = (const f32x2*)(Rl + s * 64 + cg * 8);
;         f32x2 o[20];
; #pragma unroll
;         for (int i = 0; i < 4; ++i) { o[i] = a2[i]; o[4 + i] = w2[i]; o[8 + i] = b2[i]; o[12 + i] = k2[i]; o[16 + i] = r2[i]; }
;         const float vr = Vl[s * 64 + 32 * half + rp];
;         f32x2 p0 = St[0] * o[0], p1 = St[1] * o[1];
;         p0 = __builtin_elementwise_fma(St[2], o[2], p0); p1 = __builtin_elementwise_fma(St[3], o[3], p1);
;         const float sa = oct_sum((p0.x + p0.y) + (p1.x + p1.y));
;         const f32x2 sv = {sa, sa}, vv = {vr, vr};
;         f32x2 y0 = {0.f, 0.f}, y1 = {0.f, 0.f};
; #pragma unroll
;         for (int i = 0; i < 4; i += 2) {
;           St[i] = __builtin_elementwise_fma(St[i], o[4 + i], __builtin_elementwise_fma(sv, o[8 + i], vv * o[12 + i]));
;           St[i + 1] = __builtin_elementwise_fma(St[i + 1], o[5 + i], __builtin_elementwise_fma(sv, o[9 + i], vv * o[13 + i]));
;           y0 = __builtin_elementwise_fma(St[i], o[16 + i], y0);
;           y1 = __builtin_elementwise_fma(St[i + 1], o[17 + i], y1);
;         }
;         yy[s4] = oct_sum((y0.x + y0.y) + (y1.x + y1.y));
;       }
	v_pk_mul_f32 v[34:35], v[66:67], v[34:35]
	v_pk_mul_f32 v[36:37], v[64:65], v[36:37]
	v_pk_fma_f32 v[34:35], v[62:63], v[38:39], v[34:35]
	v_pk_fma_f32 v[36:37], v[60:61], v[40:41], v[36:37]
	v_pk_add_f32 v[34:35], v[34:35], v[36:37]
	v_add_f32_e32 v207, v58, v59
	v_add_f32_e32 v198, v34, v35
	v_pk_mul_f32 v[58:59], v[68:69], v[158:159] op_sel_hi:[1,0]
	v_pk_mul_f32 v[72:73], v[70:71], v[158:159] op_sel_hi:[1,0]
	ds_read_b128 v[68:71], v0 offset:11520
	v_add_f32_dpp v198, v198, v198 quad_perm:[1,0,3,2] row_mask:0xf bank_mask:0xf bound_ctrl:1
	v_add_f32_dpp v207, v207, v207 quad_perm:[1,0,3,2] row_mask:0xf bank_mask:0xf bound_ctrl:1
	v_pk_mul_f32 v[212:213], v[150:151], v[158:159] op_sel_hi:[1,0]
	v_add_f32_dpp v198, v198, v198 quad_perm:[2,3,0,1] row_mask:0xf bank_mask:0xf bound_ctrl:1
	v_add_f32_dpp v207, v207, v207 quad_perm:[2,3,0,1] row_mask:0xf bank_mask:0xf bound_ctrl:1
	v_pk_mul_f32 v[250:251], v[152:153], v[158:159] op_sel_hi:[1,0]
	ds_read_b128 v[150:153], v0 offset:11536
	v_add_f32_dpp v198, v198, v198 row_half_mirror row_mask:0xf bank_mask:0xf bound_ctrl:1
	v_add_f32_dpp v205, v207, v207 row_half_mirror row_mask:0xf bank_mask:0xf bound_ctrl:1
	ds_write_b32 v162, v205 offset:1408
	s_waitcnt lgkmcnt(4)
	v_pk_fma_f32 v[58:59], v[198:199], v[50:51], v[58:59] op_sel_hi:[0,1,1]
	v_pk_fma_f32 v[72:73], v[198:199], v[52:53], v[72:73] op_sel_hi:[0,1,1]
	v_pk_fma_f32 v[66:67], v[66:67], v[42:43], v[58:59]
	v_pk_fma_f32 v[64:65], v[64:65], v[44:45], v[72:73]
	v_pk_fma_f32 v[212:213], v[198:199], v[54:55], v[212:213] op_sel_hi:[0,1,1]
	v_pk_fma_f32 v[250:251], v[198:199], v[56:57], v[250:251] op_sel_hi:[0,1,1]
	v_pk_fma_f32 v[62:63], v[62:63], v[46:47], v[212:213]
	v_pk_fma_f32 v[60:61], v[60:61], v[48:49], v[250:251]
	ds_read_b128 v[50:53], v0 offset:23808
	ds_read_b128 v[54:57], v0 offset:23824
	ds_read_b128 v[42:45], v0 offset:7424
	ds_read_b128 v[46:49], v0 offset:7440
	v_pk_fma_f32 v[58:59], v[66:67], v[154:155], 0 op_sel_hi:[1,1,0]
	v_pk_fma_f32 v[72:73], v[64:65], v[156:157], 0 op_sel_hi:[1,1,0]
	v_pk_fma_f32 v[58:59], v[62:63], v[246:247], v[58:59]
	v_pk_fma_f32 v[72:73], v[60:61], v[248:249], v[72:73]
	ds_read_b128 v[154:157], v0 offset:3328
	ds_read_b128 v[246:249], v0 offset:3344
	v_pk_add_f32 v[58:59], v[58:59], v[72:73]
	ds_read_b128 v[34:37], v0 offset:19968
	ds_read_b128 v[38:41], v0 offset:19984
	s_waitcnt lgkmcnt(8)
	v_pk_mul_f32 v[200:201], v[66:67], v[200:201]
	v_pk_mul_f32 v[202:203], v[64:65], v[202:203]
	v_pk_fma_f32 v[200:201], v[62:63], v[230:231], v[200:201]
	v_pk_fma_f32 v[202:203], v[60:61], v[232:233], v[202:203]
	v_pk_add_f32 v[200:201], v[200:201], v[202:203]
	v_add_f32_e32 v207, v58, v59
	v_add_f32_e32 v198, v200, v201
	v_mov_b32_e32 v232, v159
	v_pk_mul_f32 v[58:59], v[68:69], v[232:233] op_sel_hi:[1,0]
	v_pk_mul_f32 v[72:73], v[70:71], v[232:233] op_sel_hi:[1,0]
	ds_read_b128 v[68:71], v0 offset:11776
	v_add_f32_dpp v198, v198, v198 quad_perm:[1,0,3,2] row_mask:0xf bank_mask:0xf bound_ctrl:1
	v_add_f32_dpp v207, v207, v207 quad_perm:[1,0,3,2] row_mask:0xf bank_mask:0xf bound_ctrl:1
	v_pk_mul_f32 v[212:213], v[150:151], v[232:233] op_sel_hi:[1,0]
	v_add_f32_dpp v198, v198, v198 quad_perm:[2,3,0,1] row_mask:0xf bank_mask:0xf bound_ctrl:1
	v_add_f32_dpp v207, v207, v207 quad_perm:[2,3,0,1] row_mask:0xf bank_mask:0xf bound_ctrl:1
	v_pk_mul_f32 v[250:251], v[152:153], v[232:233] op_sel_hi:[1,0]
	ds_read_b128 v[150:153], v0 offset:11792
	v_add_f32_dpp v198, v198, v198 row_half_mirror row_mask:0xf bank_mask:0xf bound_ctrl:1
	v_add_f32_dpp v163, v207, v207 row_half_mirror row_mask:0xf bank_mask:0xf bound_ctrl:1
	ds_read2st64_b32 v[158:159], v161 offset0:14 offset1:15
	ds_write_b32 v162, v163 offset:1536
	s_waitcnt lgkmcnt(5)
	v_pk_fma_f32 v[58:59], v[198:199], v[50:51], v[58:59] op_sel_hi:[0,1,1]
	v_pk_fma_f32 v[72:73], v[198:199], v[52:53], v[72:73] op_sel_hi:[0,1,1]
	v_pk_fma_f32 v[66:67], v[66:67], v[42:43], v[58:59]
	v_pk_fma_f32 v[64:65], v[64:65], v[44:45], v[72:73]
	v_pk_fma_f32 v[212:213], v[198:199], v[54:55], v[212:213] op_sel_hi:[0,1,1]
	v_pk_fma_f32 v[250:251], v[198:199], v[56:57], v[250:251] op_sel_hi:[0,1,1]
	v_pk_fma_f32 v[62:63], v[62:63], v[46:47], v[212:213]
	v_pk_fma_f32 v[60:61], v[60:61], v[48:49], v[250:251]
	ds_read_b128 v[50:53], v0 offset:24064
	ds_read_b128 v[54:57], v0 offset:24080
	ds_read_b128 v[42:45], v0 offset:7680
	ds_read_b128 v[46:49], v0 offset:7696
	v_pk_fma_f32 v[58:59], v[66:67], v[154:155], 0 op_sel_hi:[1,1,0]
	v_pk_fma_f32 v[72:73], v[64:65], v[156:157], 0 op_sel_hi:[1,1,0]
	v_pk_fma_f32 v[58:59], v[62:63], v[246:247], v[58:59]
	v_pk_fma_f32 v[72:73], v[60:61], v[248:249], v[72:73]
	ds_read_b128 v[154:157], v0 offset:3584
	ds_read_b128 v[246:249], v0 offset:3600
	v_pk_add_f32 v[58:59], v[58:59], v[72:73]
	ds_read_b128 v[200:203], v0 offset:20224
	ds_read_b128 v[230:233], v0 offset:20240
	s_waitcnt lgkmcnt(8)
; DI float oct_sum(float v) { v += dpp_f<0xB1>(v); v += dpp_f<0x4E>(v); v += dpp_f<0x141>(v); return v; }
; DI void scan_item(const Params& p, int b, int h, int half, char* smem, unsigned* pgen, unsigned kp) {
;     ...
;       for (int s4 = 0; s4 < 4; ++s4) {
;         const int s = sg + s4;
;         const f32x2* a2 = (const f32x2*)(Al + s * 64 + cg * 8);
;         const f32x2* w2 = (const f32x2*)(Wl + s * 64 + cg * 8);
;         const f32x2* b2 = (const f32x2*)(Bl + s * 64 + cg * 8);
;         const f32x2* k2 = (const f32x2*)(Kl + s * 64 + cg * 8);
;         const f32x2* r2 = (const f32x2*)(Rl + s * 64 + cg * 8);
;         f32x2 o[20];
; #pragma unroll
;         for (int i = 0; i < 4; ++i) { o[i] = a2[i]; o[4 + i] = w2[i]; o[8 + i] = b2[i]; o[12 + i] = k2[i]; o[16 + i] = r2[i]; }
;         const float vr = Vl[s * 64 + 32 * half + rp];
;         f32x2 p0 = St[0] * o[0], p1 = St[1] * o[1];
;         p0 = __builtin_elementwise_fma(St[2], o[2], p0); p1 = __builtin_elementwise_fma(St[3], o[3], p1);
;         const float sa = oct_sum((p0.x + p0.y) + (p1.x + p1.y));
;         const f32x2 sv = {sa, sa}, vv = {vr, vr};
;         f32x2 y0 = {0.f, 0.f}, y1 = {0.f, 0.f};
; #pragma unroll
;         for (int i = 0; i < 4; i += 2) {
;           St[i] = __builtin_elementwise_fma(St[i], o[4 + i], __builtin_elementwise_fma(sv, o[8 + i], vv * o[12 + i]));
;           St[i + 1] = __builtin_elementwise_fma(St[i + 1], o[5 + i], __builtin_elementwise_fma(sv, o[9 + i], vv * o[13 + i]));
;           y0 = __builtin_elementwise_fma(St[i], o[16 + i], y0);
;           y1 = __builtin_elementwise_fma(St[i + 1], o[17 + i], y1);
;         }
;         yy[s4] = oct_sum((y0.x + y0.y) + (y1.x + y1.y));
;       }
;       if (cg == 0) {
; #pragma unroll
;         for (int s4 = 0; s4 < 4; ++s4) Yl[(sg + s4) * 32 + rp] = yy[s4];
	v_pk_mul_f32 v[34:35], v[66:67], v[34:35]
	v_pk_mul_f32 v[36:37], v[64:65], v[36:37]
	v_pk_fma_f32 v[34:35], v[62:63], v[38:39], v[34:35]
	v_pk_fma_f32 v[36:37], v[60:61], v[40:41], v[36:37]
	v_pk_add_f32 v[34:35], v[34:35], v[36:37]
	v_add_f32_e32 v207, v58, v59
	v_add_f32_e32 v198, v34, v35
	v_pk_mul_f32 v[58:59], v[68:69], v[158:159] op_sel_hi:[1,0]
	v_pk_mul_f32 v[72:73], v[70:71], v[158:159] op_sel_hi:[1,0]
	ds_read_b128 v[68:71], v0 offset:12032
	v_add_f32_dpp v198, v198, v198 quad_perm:[1,0,3,2] row_mask:0xf bank_mask:0xf bound_ctrl:1
	v_add_f32_dpp v207, v207, v207 quad_perm:[1,0,3,2] row_mask:0xf bank_mask:0xf bound_ctrl:1
	v_pk_mul_f32 v[212:213], v[150:151], v[158:159] op_sel_hi:[1,0]
	v_add_f32_dpp v198, v198, v198 quad_perm:[2,3,0,1] row_mask:0xf bank_mask:0xf bound_ctrl:1
	v_add_f32_dpp v207, v207, v207 quad_perm:[2,3,0,1] row_mask:0xf bank_mask:0xf bound_ctrl:1
	v_pk_mul_f32 v[250:251], v[152:153], v[158:159] op_sel_hi:[1,0]
	ds_read_b128 v[150:153], v0 offset:12048
	v_add_f32_dpp v198, v198, v198 row_half_mirror row_mask:0xf bank_mask:0xf bound_ctrl:1
	v_add_f32_dpp v205, v207, v207 row_half_mirror row_mask:0xf bank_mask:0xf bound_ctrl:1
	ds_write_b32 v162, v205 offset:1664
	s_waitcnt lgkmcnt(4)
	v_pk_fma_f32 v[58:59], v[198:199], v[50:51], v[58:59] op_sel_hi:[0,1,1]
	v_pk_fma_f32 v[72:73], v[198:199], v[52:53], v[72:73] op_sel_hi:[0,1,1]
	v_pk_fma_f32 v[66:67], v[66:67], v[42:43], v[58:59]
	v_pk_fma_f32 v[64:65], v[64:65], v[44:45], v[72:73]
	v_pk_fma_f32 v[212:213], v[198:199], v[54:55], v[212:213] op_sel_hi:[0,1,1]
	v_pk_fma_f32 v[250:251], v[198:199], v[56:57], v[250:251] op_sel_hi:[0,1,1]
	v_pk_fma_f32 v[62:63], v[62:63], v[46:47], v[212:213]
	v_pk_fma_f32 v[60:61], v[60:61], v[48:49], v[250:251]
	ds_read_b128 v[50:53], v0 offset:24320
	ds_read_b128 v[54:57], v0 offset:24336
	ds_read_b128 v[42:45], v0 offset:7936
	ds_read_b128 v[46:49], v0 offset:7952
	v_pk_fma_f32 v[58:59], v[66:67], v[154:155], 0 op_sel_hi:[1,1,0]
	v_pk_fma_f32 v[72:73], v[64:65], v[156:157], 0 op_sel_hi:[1,1,0]
	v_pk_fma_f32 v[58:59], v[62:63], v[246:247], v[58:59]
	v_pk_fma_f32 v[72:73], v[60:61], v[248:249], v[72:73]
	ds_read_b128 v[154:157], v0 offset:3840
	ds_read_b128 v[246:249], v0 offset:3856
	v_pk_add_f32 v[58:59], v[58:59], v[72:73]
	s_waitcnt lgkmcnt(6)
	v_pk_mul_f32 v[200:201], v[66:67], v[200:201]
	v_pk_mul_f32 v[202:203], v[64:65], v[202:203]
	v_pk_fma_f32 v[200:201], v[62:63], v[230:231], v[200:201]
	v_pk_fma_f32 v[202:203], v[60:61], v[232:233], v[202:203]
	v_pk_add_f32 v[200:201], v[200:201], v[202:203]
	v_add_f32_e32 v207, v58, v59
	v_add_f32_e32 v198, v200, v201
	v_mov_b32_e32 v232, v159
	v_pk_mul_f32 v[58:59], v[68:69], v[232:233] op_sel_hi:[1,0]
	v_pk_mul_f32 v[72:73], v[70:71], v[232:233] op_sel_hi:[1,0]
	v_add_f32_dpp v198, v198, v198 quad_perm:[1,0,3,2] row_mask:0xf bank_mask:0xf bound_ctrl:1
	v_add_f32_dpp v207, v207, v207 quad_perm:[1,0,3,2] row_mask:0xf bank_mask:0xf bound_ctrl:1
	v_pk_mul_f32 v[212:213], v[150:151], v[232:233] op_sel_hi:[1,0]
	v_add_f32_dpp v198, v198, v198 quad_perm:[2,3,0,1] row_mask:0xf bank_mask:0xf bound_ctrl:1
	v_add_f32_dpp v207, v207, v207 quad_perm:[2,3,0,1] row_mask:0xf bank_mask:0xf bound_ctrl:1
	v_pk_mul_f32 v[250:251], v[152:153], v[232:233] op_sel_hi:[1,0]
	v_add_f32_dpp v198, v198, v198 row_half_mirror row_mask:0xf bank_mask:0xf bound_ctrl:1
	v_add_f32_dpp v163, v207, v207 row_half_mirror row_mask:0xf bank_mask:0xf bound_ctrl:1
	ds_write_b32 v162, v163 offset:1792
	s_waitcnt lgkmcnt(0)
	v_pk_fma_f32 v[58:59], v[198:199], v[50:51], v[58:59] op_sel_hi:[0,1,1]
	v_pk_fma_f32 v[72:73], v[198:199], v[52:53], v[72:73] op_sel_hi:[0,1,1]
	v_pk_fma_f32 v[66:67], v[66:67], v[42:43], v[58:59]
	v_pk_fma_f32 v[64:65], v[64:65], v[44:45], v[72:73]
	v_pk_fma_f32 v[212:213], v[198:199], v[54:55], v[212:213] op_sel_hi:[0,1,1]
	v_pk_fma_f32 v[250:251], v[198:199], v[56:57], v[250:251] op_sel_hi:[0,1,1]
	v_pk_fma_f32 v[62:63], v[62:63], v[46:47], v[212:213]
	v_pk_fma_f32 v[60:61], v[60:61], v[48:49], v[250:251]
	v_pk_fma_f32 v[58:59], v[66:67], v[154:155], 0 op_sel_hi:[1,1,0]
	v_pk_fma_f32 v[72:73], v[64:65], v[156:157], 0 op_sel_hi:[1,1,0]
	v_pk_fma_f32 v[58:59], v[62:63], v[246:247], v[58:59]
	v_pk_fma_f32 v[72:73], v[60:61], v[248:249], v[72:73]
	v_pk_add_f32 v[58:59], v[58:59], v[72:73]
	s_nop 0
	v_add_f32_e32 v207, v58, v59
	s_nop 1
	v_add_f32_dpp v207, v207, v207 quad_perm:[1,0,3,2] row_mask:0xf bank_mask:0xf bound_ctrl:1
	s_nop 1
	v_add_f32_dpp v207, v207, v207 quad_perm:[2,3,0,1] row_mask:0xf bank_mask:0xf bound_ctrl:1
	s_nop 1
	v_add_f32_dpp v205, v207, v207 row_half_mirror row_mask:0xf bank_mask:0xf bound_ctrl:1
	ds_write_b32 v162, v205 offset:1920
